# st2 epilogue conv packed per batch pair (pk mul/add around the dpp fmacs), no s_nop
# speedup vs baseline: 1.0022x; 1.0022x over previous
; HD float2 cmul(float2 a, float2 b){ return make_float2(a.x*b.x - a.y*b.y, a.x*b.y + a.y*b.x); }
; HD float2 cmulc(float2 a, float2 b){ return make_float2(a.x*b.x + a.y*b.y, a.y*b.x - a.x*b.y); }
; template<bool INV, bool NOTW>
; HD void bf4c(float2* Z, int i0, int i1, int i2, int i3, float2 w1, float2 w2, float2 w3){
;   float2 a0=Z[i0], a1=Z[i1], a2=Z[i2], a3=Z[i3];
;   if (INV && !NOTW){ a1=cmulc(a1,w1); a2=cmulc(a2,w2); a3=cmulc(a3,w3); }
;   float2 s02=make_float2(a0.x+a2.x,a0.y+a2.y), d02=make_float2(a0.x-a2.x,a0.y-a2.y);
;   float2 s13=make_float2(a1.x+a3.x,a1.y+a3.y), d13=make_float2(a1.x-a3.x,a1.y-a3.y);
;   float2 y0=make_float2(s02.x+s13.x,s02.y+s13.y), y2=make_float2(s02.x-s13.x,s02.y-s13.y);
;   float2 ym=make_float2(d02.x+d13.y,d02.y-d13.x);
;   float2 yp=make_float2(d02.x-d13.y,d02.y+d13.x);
;   float2 y1, y3;
;   if (INV){ y1=yp; y3=ym; } else if (NOTW){ y1=ym; y3=yp; } else { y1=cmul(ym,w1); y2=cmul(y2,w2); y3=cmul(yp,w3); }
;   Z[i0]=y0; Z[i1]=y1; Z[i2]=y2; Z[i3]=y3;
; }
; template<bool INV, int LQ, bool BARRIER=true>
; HD void fft_pass(float2* Z, const float2* twA, const float2* twB, int tid){
;     ...
;   } else {
;     int j=tid&(q-1); int base0=((tid>>LQ)<<(LQ+2))+j;
;     float2 w1=make_float2(1.f,0.f), w2=w1, w3=w1;
;     if (LQ>0){ int k=j*tws; w1=cmul(twA[k>>6],twB[k&63]); w2=cmul(w1,w1); w3=cmul(w2,w1); }
;     _Pragma("unroll") for (int i=0;i<8;++i){ int base=base0+i*2048; bf4c<INV,(LQ==0)>(Z,base,base+q,base+2*q,base+3*q,w1,w2,w3); }
;   }
;   if (BARRIER) __syncthreads(); else asm volatile("s_waitcnt lgkmcnt(0)" ::: "memory");
; }
; __device__ __forceinline__ void fft_fwd_head(float2* Z, const float2* twA, const float2* twB, int tid){
;   fft_pass<false,10>(Z,twA,twB,tid); fft_pass<false,8>(Z,twA,twB,tid); fft_pass<false,6,false>(Z,twA,twB,tid);
;   fft_pass<false,4,false>(Z,twA,twB,tid); fft_pass<false,2,false>(Z,twA,twB,tid);
; }
; __device__ __forceinline__ void fft_inv_tail(float2* Z, const float2* twA, const float2* twB, int tid){
;   fft_pass<true,2,false>(Z,twA,twB,tid); fft_pass<true,4,false>(Z,twA,twB,tid); fft_pass<true,6>(Z,twA,twB,tid);
.Lmy_pf_st1:
	s_add_u32 s98, s98, 0x1000000
	s_addc_u32 s99, s99, 0
	global_load_dwordx4 v[228:231], v232, s[98:99]
	global_load_dwordx4 v[228:231], v233, s[98:99]
	global_load_dwordx4 v[228:231], v234, s[98:99]
	global_load_dwordx4 v[228:231], v235, s[98:99]
	s_waitcnt lgkmcnt(0)
	v_mov_b32_e32 v222, 0x3f6c835e
	v_mov_b32_e32 v223, 0x3ec3ef15
	v_mov_b32_e32 v224, 0x3f3504f3
	v_mov_b32_e32 v225, 0x3f3504f3
	v_and_b32_e32 v8, 15, v154
	v_lshlrev_b32_e32 v9, 3, v8
	v_add_u32_e32 v9, 0x20800, v9
	v_mov_b32_e32 v10, 0x20a00
	ds_read_b64 v[0:1], v9
	ds_read_b64 v[2:3], v10
	s_waitcnt lgkmcnt(0)
	v_pk_mul_f32 v[250:251], v[0:1], v[2:3] op_sel:[1,1] op_sel_hi:[1,0]
	v_pk_fma_f32 v[80:81], v[0:1], v[2:3], v[250:251] op_sel:[0,0,0] op_sel_hi:[0,1,1] neg_lo:[0,0,1]
	v_pk_mul_f32 v[250:251], v[80:81], v[80:81] op_sel:[1,1] op_sel_hi:[1,0]
	v_pk_fma_f32 v[82:83], v[80:81], v[80:81], v[250:251] op_sel:[0,0,0] op_sel_hi:[0,1,1] neg_lo:[0,0,1]
	v_pk_mul_f32 v[250:251], v[82:83], v[80:81] op_sel:[1,1] op_sel_hi:[1,0]
	v_pk_fma_f32 v[84:85], v[82:83], v[80:81], v[250:251] op_sel:[0,0,0] op_sel_hi:[0,1,1] neg_lo:[0,0,1]
	v_lshlrev_b32_e32 v9, 5, v8
	v_add_u32_e32 v9, 0x20800, v9
	v_mov_b32_e32 v10, 0x20a00
	ds_read_b64 v[0:1], v9
	ds_read_b64 v[2:3], v10
	s_waitcnt lgkmcnt(0)
	v_pk_mul_f32 v[250:251], v[0:1], v[2:3] op_sel:[1,1] op_sel_hi:[1,0]
	v_pk_fma_f32 v[236:237], v[0:1], v[2:3], v[250:251] op_sel:[0,0,0] op_sel_hi:[0,1,1] neg_lo:[0,0,1]
	v_pk_mul_f32 v[250:251], v[236:237], v[236:237] op_sel:[1,1] op_sel_hi:[1,0]
	v_pk_fma_f32 v[238:239], v[236:237], v[236:237], v[250:251] op_sel:[0,0,0] op_sel_hi:[0,1,1] neg_lo:[0,0,1]
	v_pk_mul_f32 v[250:251], v[238:239], v[236:237] op_sel:[1,1] op_sel_hi:[1,0]
	v_pk_fma_f32 v[240:241], v[238:239], v[236:237], v[250:251] op_sel:[0,0,0] op_sel_hi:[0,1,1] neg_lo:[0,0,1]
	v_lshrrev_b32_e32 v226, 6, v154
	v_bfe_u32 v227, v154, 4, 2
	v_lshl_add_u32 v226, v227, 3, v226
	v_lshlrev_b32_e32 v226, 8, v226
	v_and_b32_e32 v227, 15, v154
	v_add_u32_e32 v226, v226, v227
	v_lshlrev_b32_e32 v226, 3, v226
	v_add_u32_e32 v227, 0x10000, v226
	ds_read_b64 v[0:1], v226 offset:0
	ds_read_b64 v[2:3], v226 offset:128
	ds_read_b64 v[4:5], v226 offset:256
	ds_read_b64 v[6:7], v226 offset:384
	ds_read_b64 v[8:9], v226 offset:512
	ds_read_b64 v[10:11], v226 offset:640
	ds_read_b64 v[12:13], v226 offset:768
	ds_read_b64 v[14:15], v226 offset:896
	ds_read_b64 v[16:17], v226 offset:1024
	ds_read_b64 v[18:19], v226 offset:1152
	ds_read_b64 v[20:21], v226 offset:1280
	ds_read_b64 v[22:23], v226 offset:1408
	ds_read_b64 v[24:25], v226 offset:1536
	ds_read_b64 v[26:27], v226 offset:1664
	ds_read_b64 v[28:29], v226 offset:1792
	ds_read_b64 v[30:31], v226 offset:1920
	s_waitcnt lgkmcnt(12)
	v_pk_mul_f32 v[250:251], v[4:5], v[238:239] op_sel:[1,1] op_sel_hi:[0,1]
	v_pk_fma_f32 v[4:5], v[4:5], v[238:239], v[250:251] op_sel:[0,0,0] op_sel_hi:[1,0,1] neg_hi:[0,0,1]
	v_pk_mul_f32 v[250:251], v[2:3], v[236:237] op_sel:[1,1] op_sel_hi:[0,1]
	v_pk_fma_f32 v[2:3], v[2:3], v[236:237], v[250:251] op_sel:[0,0,0] op_sel_hi:[1,0,1] neg_hi:[0,0,1]
	v_pk_mul_f32 v[250:251], v[6:7], v[240:241] op_sel:[1,1] op_sel_hi:[0,1]
	v_pk_fma_f32 v[6:7], v[6:7], v[240:241], v[250:251] op_sel:[0,0,0] op_sel_hi:[1,0,1] neg_hi:[0,0,1]
	v_pk_add_f32 v[242:243], v[0:1], v[4:5]
	v_pk_add_f32 v[244:245], v[0:1], v[4:5] neg_lo:[0,1] neg_hi:[0,1]
	v_pk_add_f32 v[246:247], v[2:3], v[6:7]
	v_pk_add_f32 v[248:249], v[2:3], v[6:7] neg_lo:[0,1] neg_hi:[0,1]
	v_pk_add_f32 v[0:1], v[242:243], v[246:247]
	v_pk_add_f32 v[2:3], v[244:245], v[248:249] op_sel:[0,1] op_sel_hi:[1,0] neg_lo:[0,1]
	v_pk_add_f32 v[4:5], v[242:243], v[246:247] neg_lo:[0,1] neg_hi:[0,1]
	v_pk_add_f32 v[6:7], v[244:245], v[248:249] op_sel:[0,1] op_sel_hi:[1,0] neg_hi:[0,1]
	s_waitcnt lgkmcnt(8)
	v_pk_mul_f32 v[250:251], v[12:13], v[238:239] op_sel:[1,1] op_sel_hi:[0,1]
	v_pk_fma_f32 v[12:13], v[12:13], v[238:239], v[250:251] op_sel:[0,0,0] op_sel_hi:[1,0,1] neg_hi:[0,0,1]
	v_pk_mul_f32 v[250:251], v[10:11], v[236:237] op_sel:[1,1] op_sel_hi:[0,1]
	v_pk_fma_f32 v[10:11], v[10:11], v[236:237], v[250:251] op_sel:[0,0,0] op_sel_hi:[1,0,1] neg_hi:[0,0,1]
	v_pk_mul_f32 v[250:251], v[14:15], v[240:241] op_sel:[1,1] op_sel_hi:[0,1]
	v_pk_fma_f32 v[14:15], v[14:15], v[240:241], v[250:251] op_sel:[0,0,0] op_sel_hi:[1,0,1] neg_hi:[0,0,1]
	v_pk_add_f32 v[242:243], v[8:9], v[12:13]
	v_pk_add_f32 v[244:245], v[8:9], v[12:13] neg_lo:[0,1] neg_hi:[0,1]
	v_pk_add_f32 v[246:247], v[10:11], v[14:15]
	v_pk_add_f32 v[248:249], v[10:11], v[14:15] neg_lo:[0,1] neg_hi:[0,1]
	v_pk_add_f32 v[8:9], v[242:243], v[246:247]
	v_pk_add_f32 v[10:11], v[244:245], v[248:249] op_sel:[0,1] op_sel_hi:[1,0] neg_lo:[0,1]
	v_pk_add_f32 v[12:13], v[242:243], v[246:247] neg_lo:[0,1] neg_hi:[0,1]
	v_pk_add_f32 v[14:15], v[244:245], v[248:249] op_sel:[0,1] op_sel_hi:[1,0] neg_hi:[0,1]
	s_waitcnt lgkmcnt(4)
	v_pk_mul_f32 v[250:251], v[20:21], v[238:239] op_sel:[1,1] op_sel_hi:[0,1]
	v_pk_fma_f32 v[20:21], v[20:21], v[238:239], v[250:251] op_sel:[0,0,0] op_sel_hi:[1,0,1] neg_hi:[0,0,1]
	v_pk_mul_f32 v[250:251], v[18:19], v[236:237] op_sel:[1,1] op_sel_hi:[0,1]
	v_pk_fma_f32 v[18:19], v[18:19], v[236:237], v[250:251] op_sel:[0,0,0] op_sel_hi:[1,0,1] neg_hi:[0,0,1]
	v_pk_mul_f32 v[250:251], v[22:23], v[240:241] op_sel:[1,1] op_sel_hi:[0,1]
	v_pk_fma_f32 v[22:23], v[22:23], v[240:241], v[250:251] op_sel:[0,0,0] op_sel_hi:[1,0,1] neg_hi:[0,0,1]
	v_pk_add_f32 v[242:243], v[16:17], v[20:21]
	v_pk_add_f32 v[244:245], v[16:17], v[20:21] neg_lo:[0,1] neg_hi:[0,1]
	v_pk_add_f32 v[246:247], v[18:19], v[22:23]
	v_pk_add_f32 v[248:249], v[18:19], v[22:23] neg_lo:[0,1] neg_hi:[0,1]
	v_pk_add_f32 v[16:17], v[242:243], v[246:247]
	v_pk_add_f32 v[18:19], v[244:245], v[248:249] op_sel:[0,1] op_sel_hi:[1,0] neg_lo:[0,1]
	v_pk_add_f32 v[20:21], v[242:243], v[246:247] neg_lo:[0,1] neg_hi:[0,1]
	v_pk_add_f32 v[22:23], v[244:245], v[248:249] op_sel:[0,1] op_sel_hi:[1,0] neg_hi:[0,1]
	s_waitcnt lgkmcnt(0)
; HD float2 cmul(float2 a, float2 b){ return make_float2(a.x*b.x - a.y*b.y, a.x*b.y + a.y*b.x); }
; HD float2 cmulc(float2 a, float2 b){ return make_float2(a.x*b.x + a.y*b.y, a.y*b.x - a.x*b.y); }
; template<bool INV, bool NOTW>
; HD void bf4c(float2* Z, int i0, int i1, int i2, int i3, float2 w1, float2 w2, float2 w3){
;   float2 a0=Z[i0], a1=Z[i1], a2=Z[i2], a3=Z[i3];
;   if (INV && !NOTW){ a1=cmulc(a1,w1); a2=cmulc(a2,w2); a3=cmulc(a3,w3); }
;   float2 s02=make_float2(a0.x+a2.x,a0.y+a2.y), d02=make_float2(a0.x-a2.x,a0.y-a2.y);
;   float2 s13=make_float2(a1.x+a3.x,a1.y+a3.y), d13=make_float2(a1.x-a3.x,a1.y-a3.y);
;   float2 y0=make_float2(s02.x+s13.x,s02.y+s13.y), y2=make_float2(s02.x-s13.x,s02.y-s13.y);
;   float2 ym=make_float2(d02.x+d13.y,d02.y-d13.x);
;   float2 yp=make_float2(d02.x-d13.y,d02.y+d13.x);
;   float2 y1, y3;
;   if (INV){ y1=yp; y3=ym; } else if (NOTW){ y1=ym; y3=yp; } else { y1=cmul(ym,w1); y2=cmul(y2,w2); y3=cmul(yp,w3); }
;   Z[i0]=y0; Z[i1]=y1; Z[i2]=y2; Z[i3]=y3;
; }
; template<bool INV, int LQ, bool BARRIER=true>
; HD void fft_pass(float2* Z, const float2* twA, const float2* twB, int tid){
;     ...
;   } else {
;     int j=tid&(q-1); int base0=((tid>>LQ)<<(LQ+2))+j;
;     float2 w1=make_float2(1.f,0.f), w2=w1, w3=w1;
;     if (LQ>0){ int k=j*tws; w1=cmul(twA[k>>6],twB[k&63]); w2=cmul(w1,w1); w3=cmul(w2,w1); }
;     _Pragma("unroll") for (int i=0;i<8;++i){ int base=base0+i*2048; bf4c<INV,(LQ==0)>(Z,base,base+q,base+2*q,base+3*q,w1,w2,w3); }
;   }
;   if (BARRIER) __syncthreads(); else asm volatile("s_waitcnt lgkmcnt(0)" ::: "memory");
; }
; __device__ __forceinline__ void fft_fwd_head(float2* Z, const float2* twA, const float2* twB, int tid){
;   fft_pass<false,10>(Z,twA,twB,tid); fft_pass<false,8>(Z,twA,twB,tid); fft_pass<false,6,false>(Z,twA,twB,tid);
;   fft_pass<false,4,false>(Z,twA,twB,tid); fft_pass<false,2,false>(Z,twA,twB,tid);
; }
; __device__ __forceinline__ void fft_inv_tail(float2* Z, const float2* twA, const float2* twB, int tid){
;   fft_pass<true,2,false>(Z,twA,twB,tid); fft_pass<true,4,false>(Z,twA,twB,tid); fft_pass<true,6>(Z,twA,twB,tid);
	v_pk_mul_f32 v[250:251], v[28:29], v[238:239] op_sel:[1,1] op_sel_hi:[0,1]
	v_pk_fma_f32 v[28:29], v[28:29], v[238:239], v[250:251] op_sel:[0,0,0] op_sel_hi:[1,0,1] neg_hi:[0,0,1]
	v_pk_mul_f32 v[250:251], v[26:27], v[236:237] op_sel:[1,1] op_sel_hi:[0,1]
	v_pk_fma_f32 v[26:27], v[26:27], v[236:237], v[250:251] op_sel:[0,0,0] op_sel_hi:[1,0,1] neg_hi:[0,0,1]
	v_pk_mul_f32 v[250:251], v[30:31], v[240:241] op_sel:[1,1] op_sel_hi:[0,1]
	v_pk_fma_f32 v[30:31], v[30:31], v[240:241], v[250:251] op_sel:[0,0,0] op_sel_hi:[1,0,1] neg_hi:[0,0,1]
	v_pk_add_f32 v[242:243], v[24:25], v[28:29]
	v_pk_add_f32 v[244:245], v[24:25], v[28:29] neg_lo:[0,1] neg_hi:[0,1]
	v_pk_add_f32 v[246:247], v[26:27], v[30:31]
	v_pk_add_f32 v[248:249], v[26:27], v[30:31] neg_lo:[0,1] neg_hi:[0,1]
	v_pk_add_f32 v[24:25], v[242:243], v[246:247]
	v_pk_add_f32 v[26:27], v[244:245], v[248:249] op_sel:[0,1] op_sel_hi:[1,0] neg_lo:[0,1]
	v_pk_add_f32 v[28:29], v[242:243], v[246:247] neg_lo:[0,1] neg_hi:[0,1]
	v_pk_add_f32 v[30:31], v[244:245], v[248:249] op_sel:[0,1] op_sel_hi:[1,0] neg_hi:[0,1]
	v_pk_mul_f32 v[250:251], v[16:17], v[82:83] op_sel:[1,1] op_sel_hi:[0,1]
	v_pk_fma_f32 v[16:17], v[16:17], v[82:83], v[250:251] op_sel:[0,0,0] op_sel_hi:[1,0,1] neg_hi:[0,0,1]
	v_pk_mul_f32 v[250:251], v[8:9], v[80:81] op_sel:[1,1] op_sel_hi:[0,1]
	v_pk_fma_f32 v[8:9], v[8:9], v[80:81], v[250:251] op_sel:[0,0,0] op_sel_hi:[1,0,1] neg_hi:[0,0,1]
	v_pk_mul_f32 v[250:251], v[24:25], v[84:85] op_sel:[1,1] op_sel_hi:[0,1]
	v_pk_fma_f32 v[24:25], v[24:25], v[84:85], v[250:251] op_sel:[0,0,0] op_sel_hi:[1,0,1] neg_hi:[0,0,1]
	v_pk_add_f32 v[242:243], v[0:1], v[16:17]
	v_pk_add_f32 v[244:245], v[0:1], v[16:17] neg_lo:[0,1] neg_hi:[0,1]
	v_pk_add_f32 v[246:247], v[8:9], v[24:25]
	v_pk_add_f32 v[248:249], v[8:9], v[24:25] neg_lo:[0,1] neg_hi:[0,1]
	v_pk_add_f32 v[0:1], v[242:243], v[246:247]
	ds_write_b64 v226, v[0:1] offset:0
	v_pk_add_f32 v[8:9], v[244:245], v[248:249] op_sel:[0,1] op_sel_hi:[1,0] neg_lo:[0,1]
	ds_write_b64 v226, v[8:9] offset:512
	v_pk_add_f32 v[16:17], v[242:243], v[246:247] neg_lo:[0,1] neg_hi:[0,1]
	ds_write_b64 v226, v[16:17] offset:1024
	v_pk_add_f32 v[24:25], v[244:245], v[248:249] op_sel:[0,1] op_sel_hi:[1,0] neg_hi:[0,1]
	ds_write_b64 v226, v[24:25] offset:1536
	v_pk_mul_f32 v[250:251], v[18:19], v[224:225] op_sel:[1,1] op_sel_hi:[1,0] neg_lo:[0,0] neg_hi:[0,0]
	v_pk_fma_f32 v[18:19], v[18:19], v[224:225], v[250:251] op_sel:[0,0,0] op_sel_hi:[0,1,1] neg_lo:[0,0,1] neg_hi:[0,0,0]
	v_pk_mul_f32 v[250:251], v[18:19], v[82:83] op_sel:[1,1] op_sel_hi:[0,1]
	v_pk_fma_f32 v[18:19], v[18:19], v[82:83], v[250:251] op_sel:[0,0,0] op_sel_hi:[1,0,1] neg_hi:[0,0,1]
	v_pk_mul_f32 v[250:251], v[10:11], v[222:223] op_sel:[1,1] op_sel_hi:[1,0] neg_lo:[0,0] neg_hi:[0,0]
	v_pk_fma_f32 v[10:11], v[10:11], v[222:223], v[250:251] op_sel:[0,0,0] op_sel_hi:[0,1,1] neg_lo:[0,0,1] neg_hi:[0,0,0]
	v_pk_mul_f32 v[250:251], v[10:11], v[80:81] op_sel:[1,1] op_sel_hi:[0,1]
	v_pk_fma_f32 v[10:11], v[10:11], v[80:81], v[250:251] op_sel:[0,0,0] op_sel_hi:[1,0,1] neg_hi:[0,0,1]
	v_pk_mul_f32 v[250:251], v[26:27], v[222:223] op_sel:[1,0] op_sel_hi:[1,1] neg_lo:[0,0] neg_hi:[0,0]
	v_pk_fma_f32 v[26:27], v[26:27], v[222:223], v[250:251] op_sel:[0,1,0] op_sel_hi:[0,0,1] neg_lo:[0,0,1] neg_hi:[0,0,0]
	v_pk_mul_f32 v[250:251], v[26:27], v[84:85] op_sel:[1,1] op_sel_hi:[0,1]
	v_pk_fma_f32 v[26:27], v[26:27], v[84:85], v[250:251] op_sel:[0,0,0] op_sel_hi:[1,0,1] neg_hi:[0,0,1]
	v_pk_add_f32 v[242:243], v[2:3], v[18:19]
	v_pk_add_f32 v[244:245], v[2:3], v[18:19] neg_lo:[0,1] neg_hi:[0,1]
	v_pk_add_f32 v[246:247], v[10:11], v[26:27]
	v_pk_add_f32 v[248:249], v[10:11], v[26:27] neg_lo:[0,1] neg_hi:[0,1]
	v_pk_add_f32 v[2:3], v[242:243], v[246:247]
	ds_write_b64 v226, v[2:3] offset:128
	v_pk_add_f32 v[10:11], v[244:245], v[248:249] op_sel:[0,1] op_sel_hi:[1,0] neg_lo:[0,1]
	ds_write_b64 v226, v[10:11] offset:640
	v_pk_add_f32 v[18:19], v[242:243], v[246:247] neg_lo:[0,1] neg_hi:[0,1]
	ds_write_b64 v226, v[18:19] offset:1152
	v_pk_add_f32 v[26:27], v[244:245], v[248:249] op_sel:[0,1] op_sel_hi:[1,0] neg_hi:[0,1]
	ds_write_b64 v226, v[26:27] offset:1664
	v_pk_add_f32 v[20:21], v[20:21], 0 op_sel:[1,0] op_sel_hi:[0,0] neg_lo:[1,0]
	v_pk_mul_f32 v[250:251], v[20:21], v[82:83] op_sel:[1,1] op_sel_hi:[0,1]
	v_pk_fma_f32 v[20:21], v[20:21], v[82:83], v[250:251] op_sel:[0,0,0] op_sel_hi:[1,0,1] neg_hi:[0,0,1]
	v_pk_mul_f32 v[250:251], v[12:13], v[224:225] op_sel:[1,1] op_sel_hi:[1,0] neg_lo:[0,0] neg_hi:[0,0]
	v_pk_fma_f32 v[12:13], v[12:13], v[224:225], v[250:251] op_sel:[0,0,0] op_sel_hi:[0,1,1] neg_lo:[0,0,1] neg_hi:[0,0,0]
	v_pk_mul_f32 v[250:251], v[12:13], v[80:81] op_sel:[1,1] op_sel_hi:[0,1]
	v_pk_fma_f32 v[12:13], v[12:13], v[80:81], v[250:251] op_sel:[0,0,0] op_sel_hi:[1,0,1] neg_hi:[0,0,1]
	v_pk_mul_f32 v[250:251], v[28:29], v[224:225] op_sel:[1,1] op_sel_hi:[1,0] neg_lo:[0,0] neg_hi:[0,1]
	v_pk_fma_f32 v[28:29], v[28:29], v[224:225], v[250:251] op_sel:[0,0,0] op_sel_hi:[0,1,1] neg_lo:[0,1,1] neg_hi:[0,0,0]
	v_pk_mul_f32 v[250:251], v[28:29], v[84:85] op_sel:[1,1] op_sel_hi:[0,1]
	v_pk_fma_f32 v[28:29], v[28:29], v[84:85], v[250:251] op_sel:[0,0,0] op_sel_hi:[1,0,1] neg_hi:[0,0,1]
	v_pk_add_f32 v[242:243], v[4:5], v[20:21]
	v_pk_add_f32 v[244:245], v[4:5], v[20:21] neg_lo:[0,1] neg_hi:[0,1]
	v_pk_add_f32 v[246:247], v[12:13], v[28:29]
	v_pk_add_f32 v[248:249], v[12:13], v[28:29] neg_lo:[0,1] neg_hi:[0,1]
	v_pk_add_f32 v[4:5], v[242:243], v[246:247]
	ds_write_b64 v226, v[4:5] offset:256
	v_pk_add_f32 v[12:13], v[244:245], v[248:249] op_sel:[0,1] op_sel_hi:[1,0] neg_lo:[0,1]
	ds_write_b64 v226, v[12:13] offset:768
; HD float2 cmul(float2 a, float2 b){ return make_float2(a.x*b.x - a.y*b.y, a.x*b.y + a.y*b.x); }
; HD float2 cmulc(float2 a, float2 b){ return make_float2(a.x*b.x + a.y*b.y, a.y*b.x - a.x*b.y); }
; template<bool INV, bool NOTW>
; HD void bf4c(float2* Z, int i0, int i1, int i2, int i3, float2 w1, float2 w2, float2 w3){
;   float2 a0=Z[i0], a1=Z[i1], a2=Z[i2], a3=Z[i3];
;   if (INV && !NOTW){ a1=cmulc(a1,w1); a2=cmulc(a2,w2); a3=cmulc(a3,w3); }
;   float2 s02=make_float2(a0.x+a2.x,a0.y+a2.y), d02=make_float2(a0.x-a2.x,a0.y-a2.y);
;   float2 s13=make_float2(a1.x+a3.x,a1.y+a3.y), d13=make_float2(a1.x-a3.x,a1.y-a3.y);
;   float2 y0=make_float2(s02.x+s13.x,s02.y+s13.y), y2=make_float2(s02.x-s13.x,s02.y-s13.y);
;   float2 ym=make_float2(d02.x+d13.y,d02.y-d13.x);
;   float2 yp=make_float2(d02.x-d13.y,d02.y+d13.x);
;   float2 y1, y3;
;   if (INV){ y1=yp; y3=ym; } else if (NOTW){ y1=ym; y3=yp; } else { y1=cmul(ym,w1); y2=cmul(y2,w2); y3=cmul(yp,w3); }
;   Z[i0]=y0; Z[i1]=y1; Z[i2]=y2; Z[i3]=y3;
; }
; template<bool INV, int LQ, bool BARRIER=true>
; HD void fft_pass(float2* Z, const float2* twA, const float2* twB, int tid){
;     ...
;   } else {
;     int j=tid&(q-1); int base0=((tid>>LQ)<<(LQ+2))+j;
;     float2 w1=make_float2(1.f,0.f), w2=w1, w3=w1;
;     if (LQ>0){ int k=j*tws; w1=cmul(twA[k>>6],twB[k&63]); w2=cmul(w1,w1); w3=cmul(w2,w1); }
;     _Pragma("unroll") for (int i=0;i<8;++i){ int base=base0+i*2048; bf4c<INV,(LQ==0)>(Z,base,base+q,base+2*q,base+3*q,w1,w2,w3); }
;   }
;   if (BARRIER) __syncthreads(); else asm volatile("s_waitcnt lgkmcnt(0)" ::: "memory");
; }
; __device__ __forceinline__ void fft_fwd_head(float2* Z, const float2* twA, const float2* twB, int tid){
;   fft_pass<false,10>(Z,twA,twB,tid); fft_pass<false,8>(Z,twA,twB,tid); fft_pass<false,6,false>(Z,twA,twB,tid);
;   fft_pass<false,4,false>(Z,twA,twB,tid); fft_pass<false,2,false>(Z,twA,twB,tid);
; }
; __device__ __forceinline__ void fft_inv_tail(float2* Z, const float2* twA, const float2* twB, int tid){
;   fft_pass<true,2,false>(Z,twA,twB,tid); fft_pass<true,4,false>(Z,twA,twB,tid); fft_pass<true,6>(Z,twA,twB,tid);
	v_pk_add_f32 v[20:21], v[242:243], v[246:247] neg_lo:[0,1] neg_hi:[0,1]
	ds_write_b64 v226, v[20:21] offset:1280
	v_pk_add_f32 v[28:29], v[244:245], v[248:249] op_sel:[0,1] op_sel_hi:[1,0] neg_hi:[0,1]
	ds_write_b64 v226, v[28:29] offset:1792
	v_pk_mul_f32 v[250:251], v[22:23], v[224:225] op_sel:[1,1] op_sel_hi:[1,0] neg_lo:[0,0] neg_hi:[0,1]
	v_pk_fma_f32 v[22:23], v[22:23], v[224:225], v[250:251] op_sel:[0,0,0] op_sel_hi:[0,1,1] neg_lo:[0,1,1] neg_hi:[0,0,0]
	v_pk_mul_f32 v[250:251], v[22:23], v[82:83] op_sel:[1,1] op_sel_hi:[0,1]
	v_pk_fma_f32 v[22:23], v[22:23], v[82:83], v[250:251] op_sel:[0,0,0] op_sel_hi:[1,0,1] neg_hi:[0,0,1]
	v_pk_mul_f32 v[250:251], v[14:15], v[222:223] op_sel:[1,0] op_sel_hi:[1,1] neg_lo:[0,0] neg_hi:[0,0]
	v_pk_fma_f32 v[14:15], v[14:15], v[222:223], v[250:251] op_sel:[0,1,0] op_sel_hi:[0,0,1] neg_lo:[0,0,1] neg_hi:[0,0,0]
	v_pk_mul_f32 v[250:251], v[14:15], v[80:81] op_sel:[1,1] op_sel_hi:[0,1]
	v_pk_fma_f32 v[14:15], v[14:15], v[80:81], v[250:251] op_sel:[0,0,0] op_sel_hi:[1,0,1] neg_hi:[0,0,1]
	v_pk_mul_f32 v[250:251], v[30:31], v[222:223] op_sel:[1,1] op_sel_hi:[1,0] neg_lo:[0,1] neg_hi:[0,1]
	v_pk_fma_f32 v[30:31], v[30:31], v[222:223], v[250:251] op_sel:[0,0,0] op_sel_hi:[0,1,1] neg_lo:[0,1,1] neg_hi:[0,1,0]
	v_pk_mul_f32 v[250:251], v[30:31], v[84:85] op_sel:[1,1] op_sel_hi:[0,1]
	v_pk_fma_f32 v[30:31], v[30:31], v[84:85], v[250:251] op_sel:[0,0,0] op_sel_hi:[1,0,1] neg_hi:[0,0,1]
	v_pk_add_f32 v[242:243], v[6:7], v[22:23]
	v_pk_add_f32 v[244:245], v[6:7], v[22:23] neg_lo:[0,1] neg_hi:[0,1]
	v_pk_add_f32 v[246:247], v[14:15], v[30:31]
	v_pk_add_f32 v[248:249], v[14:15], v[30:31] neg_lo:[0,1] neg_hi:[0,1]
	v_pk_add_f32 v[6:7], v[242:243], v[246:247]
	ds_write_b64 v226, v[6:7] offset:384
	v_pk_add_f32 v[14:15], v[244:245], v[248:249] op_sel:[0,1] op_sel_hi:[1,0] neg_lo:[0,1]
	ds_write_b64 v226, v[14:15] offset:896
	v_pk_add_f32 v[22:23], v[242:243], v[246:247] neg_lo:[0,1] neg_hi:[0,1]
	ds_write_b64 v226, v[22:23] offset:1408
	v_pk_add_f32 v[30:31], v[244:245], v[248:249] op_sel:[0,1] op_sel_hi:[1,0] neg_hi:[0,1]
	ds_write_b64 v226, v[30:31] offset:1920
	ds_read_b64 v[0:1], v227 offset:0
	ds_read_b64 v[2:3], v227 offset:128
	ds_read_b64 v[4:5], v227 offset:256
	ds_read_b64 v[6:7], v227 offset:384
	ds_read_b64 v[8:9], v227 offset:512
	ds_read_b64 v[10:11], v227 offset:640
	ds_read_b64 v[12:13], v227 offset:768
	ds_read_b64 v[14:15], v227 offset:896
	ds_read_b64 v[16:17], v227 offset:1024
	ds_read_b64 v[18:19], v227 offset:1152
	ds_read_b64 v[20:21], v227 offset:1280
	ds_read_b64 v[22:23], v227 offset:1408
	ds_read_b64 v[24:25], v227 offset:1536
	ds_read_b64 v[26:27], v227 offset:1664
	ds_read_b64 v[28:29], v227 offset:1792
	ds_read_b64 v[30:31], v227 offset:1920
	s_waitcnt lgkmcnt(12)
	v_pk_mul_f32 v[250:251], v[4:5], v[238:239] op_sel:[1,1] op_sel_hi:[0,1]
	v_pk_fma_f32 v[4:5], v[4:5], v[238:239], v[250:251] op_sel:[0,0,0] op_sel_hi:[1,0,1] neg_hi:[0,0,1]
	v_pk_mul_f32 v[250:251], v[2:3], v[236:237] op_sel:[1,1] op_sel_hi:[0,1]
	v_pk_fma_f32 v[2:3], v[2:3], v[236:237], v[250:251] op_sel:[0,0,0] op_sel_hi:[1,0,1] neg_hi:[0,0,1]
	v_pk_mul_f32 v[250:251], v[6:7], v[240:241] op_sel:[1,1] op_sel_hi:[0,1]
	v_pk_fma_f32 v[6:7], v[6:7], v[240:241], v[250:251] op_sel:[0,0,0] op_sel_hi:[1,0,1] neg_hi:[0,0,1]
	v_pk_add_f32 v[242:243], v[0:1], v[4:5]
	v_pk_add_f32 v[244:245], v[0:1], v[4:5] neg_lo:[0,1] neg_hi:[0,1]
	v_pk_add_f32 v[246:247], v[2:3], v[6:7]
	v_pk_add_f32 v[248:249], v[2:3], v[6:7] neg_lo:[0,1] neg_hi:[0,1]
	v_pk_add_f32 v[0:1], v[242:243], v[246:247]
	v_pk_add_f32 v[2:3], v[244:245], v[248:249] op_sel:[0,1] op_sel_hi:[1,0] neg_lo:[0,1]
	v_pk_add_f32 v[4:5], v[242:243], v[246:247] neg_lo:[0,1] neg_hi:[0,1]
	v_pk_add_f32 v[6:7], v[244:245], v[248:249] op_sel:[0,1] op_sel_hi:[1,0] neg_hi:[0,1]
	s_waitcnt lgkmcnt(8)
	v_pk_mul_f32 v[250:251], v[12:13], v[238:239] op_sel:[1,1] op_sel_hi:[0,1]
	v_pk_fma_f32 v[12:13], v[12:13], v[238:239], v[250:251] op_sel:[0,0,0] op_sel_hi:[1,0,1] neg_hi:[0,0,1]
	v_pk_mul_f32 v[250:251], v[10:11], v[236:237] op_sel:[1,1] op_sel_hi:[0,1]
	v_pk_fma_f32 v[10:11], v[10:11], v[236:237], v[250:251] op_sel:[0,0,0] op_sel_hi:[1,0,1] neg_hi:[0,0,1]
	v_pk_mul_f32 v[250:251], v[14:15], v[240:241] op_sel:[1,1] op_sel_hi:[0,1]
	v_pk_fma_f32 v[14:15], v[14:15], v[240:241], v[250:251] op_sel:[0,0,0] op_sel_hi:[1,0,1] neg_hi:[0,0,1]
	v_pk_add_f32 v[242:243], v[8:9], v[12:13]
	v_pk_add_f32 v[244:245], v[8:9], v[12:13] neg_lo:[0,1] neg_hi:[0,1]
	v_pk_add_f32 v[246:247], v[10:11], v[14:15]
	v_pk_add_f32 v[248:249], v[10:11], v[14:15] neg_lo:[0,1] neg_hi:[0,1]
	v_pk_add_f32 v[8:9], v[242:243], v[246:247]
	v_pk_add_f32 v[10:11], v[244:245], v[248:249] op_sel:[0,1] op_sel_hi:[1,0] neg_lo:[0,1]
	v_pk_add_f32 v[12:13], v[242:243], v[246:247] neg_lo:[0,1] neg_hi:[0,1]
	v_pk_add_f32 v[14:15], v[244:245], v[248:249] op_sel:[0,1] op_sel_hi:[1,0] neg_hi:[0,1]
	s_waitcnt lgkmcnt(4)
	v_pk_mul_f32 v[250:251], v[20:21], v[238:239] op_sel:[1,1] op_sel_hi:[0,1]
	v_pk_fma_f32 v[20:21], v[20:21], v[238:239], v[250:251] op_sel:[0,0,0] op_sel_hi:[1,0,1] neg_hi:[0,0,1]
	v_pk_mul_f32 v[250:251], v[18:19], v[236:237] op_sel:[1,1] op_sel_hi:[0,1]
	v_pk_fma_f32 v[18:19], v[18:19], v[236:237], v[250:251] op_sel:[0,0,0] op_sel_hi:[1,0,1] neg_hi:[0,0,1]
	v_pk_mul_f32 v[250:251], v[22:23], v[240:241] op_sel:[1,1] op_sel_hi:[0,1]
	v_pk_fma_f32 v[22:23], v[22:23], v[240:241], v[250:251] op_sel:[0,0,0] op_sel_hi:[1,0,1] neg_hi:[0,0,1]
	v_pk_add_f32 v[242:243], v[16:17], v[20:21]
	v_pk_add_f32 v[244:245], v[16:17], v[20:21] neg_lo:[0,1] neg_hi:[0,1]
	v_pk_add_f32 v[246:247], v[18:19], v[22:23]
	v_pk_add_f32 v[248:249], v[18:19], v[22:23] neg_lo:[0,1] neg_hi:[0,1]
	v_pk_add_f32 v[16:17], v[242:243], v[246:247]
	v_pk_add_f32 v[18:19], v[244:245], v[248:249] op_sel:[0,1] op_sel_hi:[1,0] neg_lo:[0,1]
	v_pk_add_f32 v[20:21], v[242:243], v[246:247] neg_lo:[0,1] neg_hi:[0,1]
	v_pk_add_f32 v[22:23], v[244:245], v[248:249] op_sel:[0,1] op_sel_hi:[1,0] neg_hi:[0,1]
	s_waitcnt lgkmcnt(0)
; HD float2 cmul(float2 a, float2 b){ return make_float2(a.x*b.x - a.y*b.y, a.x*b.y + a.y*b.x); }
; HD float2 cmulc(float2 a, float2 b){ return make_float2(a.x*b.x + a.y*b.y, a.y*b.x - a.x*b.y); }
; template<bool INV, bool NOTW>
; HD void bf4c(float2* Z, int i0, int i1, int i2, int i3, float2 w1, float2 w2, float2 w3){
;   float2 a0=Z[i0], a1=Z[i1], a2=Z[i2], a3=Z[i3];
;   if (INV && !NOTW){ a1=cmulc(a1,w1); a2=cmulc(a2,w2); a3=cmulc(a3,w3); }
;   float2 s02=make_float2(a0.x+a2.x,a0.y+a2.y), d02=make_float2(a0.x-a2.x,a0.y-a2.y);
;   float2 s13=make_float2(a1.x+a3.x,a1.y+a3.y), d13=make_float2(a1.x-a3.x,a1.y-a3.y);
;   float2 y0=make_float2(s02.x+s13.x,s02.y+s13.y), y2=make_float2(s02.x-s13.x,s02.y-s13.y);
;   float2 ym=make_float2(d02.x+d13.y,d02.y-d13.x);
;   float2 yp=make_float2(d02.x-d13.y,d02.y+d13.x);
;   float2 y1, y3;
;   if (INV){ y1=yp; y3=ym; } else if (NOTW){ y1=ym; y3=yp; } else { y1=cmul(ym,w1); y2=cmul(y2,w2); y3=cmul(yp,w3); }
;   Z[i0]=y0; Z[i1]=y1; Z[i2]=y2; Z[i3]=y3;
; }
; template<bool INV, int LQ, bool BARRIER=true>
; HD void fft_pass(float2* Z, const float2* twA, const float2* twB, int tid){
;     ...
;   } else {
;     int j=tid&(q-1); int base0=((tid>>LQ)<<(LQ+2))+j;
;     float2 w1=make_float2(1.f,0.f), w2=w1, w3=w1;
;     if (LQ>0){ int k=j*tws; w1=cmul(twA[k>>6],twB[k&63]); w2=cmul(w1,w1); w3=cmul(w2,w1); }
;     _Pragma("unroll") for (int i=0;i<8;++i){ int base=base0+i*2048; bf4c<INV,(LQ==0)>(Z,base,base+q,base+2*q,base+3*q,w1,w2,w3); }
;   }
;   if (BARRIER) __syncthreads(); else asm volatile("s_waitcnt lgkmcnt(0)" ::: "memory");
; }
; __device__ __forceinline__ void fft_fwd_head(float2* Z, const float2* twA, const float2* twB, int tid){
;   fft_pass<false,10>(Z,twA,twB,tid); fft_pass<false,8>(Z,twA,twB,tid); fft_pass<false,6,false>(Z,twA,twB,tid);
;   fft_pass<false,4,false>(Z,twA,twB,tid); fft_pass<false,2,false>(Z,twA,twB,tid);
; }
; __device__ __forceinline__ void fft_inv_tail(float2* Z, const float2* twA, const float2* twB, int tid){
;   fft_pass<true,2,false>(Z,twA,twB,tid); fft_pass<true,4,false>(Z,twA,twB,tid); fft_pass<true,6>(Z,twA,twB,tid);
	v_pk_mul_f32 v[250:251], v[28:29], v[238:239] op_sel:[1,1] op_sel_hi:[0,1]
	v_pk_fma_f32 v[28:29], v[28:29], v[238:239], v[250:251] op_sel:[0,0,0] op_sel_hi:[1,0,1] neg_hi:[0,0,1]
	v_pk_mul_f32 v[250:251], v[26:27], v[236:237] op_sel:[1,1] op_sel_hi:[0,1]
	v_pk_fma_f32 v[26:27], v[26:27], v[236:237], v[250:251] op_sel:[0,0,0] op_sel_hi:[1,0,1] neg_hi:[0,0,1]
	v_pk_mul_f32 v[250:251], v[30:31], v[240:241] op_sel:[1,1] op_sel_hi:[0,1]
	v_pk_fma_f32 v[30:31], v[30:31], v[240:241], v[250:251] op_sel:[0,0,0] op_sel_hi:[1,0,1] neg_hi:[0,0,1]
	v_pk_add_f32 v[242:243], v[24:25], v[28:29]
	v_pk_add_f32 v[244:245], v[24:25], v[28:29] neg_lo:[0,1] neg_hi:[0,1]
	v_pk_add_f32 v[246:247], v[26:27], v[30:31]
	v_pk_add_f32 v[248:249], v[26:27], v[30:31] neg_lo:[0,1] neg_hi:[0,1]
	v_pk_add_f32 v[24:25], v[242:243], v[246:247]
	v_pk_add_f32 v[26:27], v[244:245], v[248:249] op_sel:[0,1] op_sel_hi:[1,0] neg_lo:[0,1]
	v_pk_add_f32 v[28:29], v[242:243], v[246:247] neg_lo:[0,1] neg_hi:[0,1]
	v_pk_add_f32 v[30:31], v[244:245], v[248:249] op_sel:[0,1] op_sel_hi:[1,0] neg_hi:[0,1]
	v_pk_mul_f32 v[250:251], v[16:17], v[82:83] op_sel:[1,1] op_sel_hi:[0,1]
	v_pk_fma_f32 v[16:17], v[16:17], v[82:83], v[250:251] op_sel:[0,0,0] op_sel_hi:[1,0,1] neg_hi:[0,0,1]
	v_pk_mul_f32 v[250:251], v[8:9], v[80:81] op_sel:[1,1] op_sel_hi:[0,1]
	v_pk_fma_f32 v[8:9], v[8:9], v[80:81], v[250:251] op_sel:[0,0,0] op_sel_hi:[1,0,1] neg_hi:[0,0,1]
	v_pk_mul_f32 v[250:251], v[24:25], v[84:85] op_sel:[1,1] op_sel_hi:[0,1]
	v_pk_fma_f32 v[24:25], v[24:25], v[84:85], v[250:251] op_sel:[0,0,0] op_sel_hi:[1,0,1] neg_hi:[0,0,1]
	v_pk_add_f32 v[242:243], v[0:1], v[16:17]
	v_pk_add_f32 v[244:245], v[0:1], v[16:17] neg_lo:[0,1] neg_hi:[0,1]
	v_pk_add_f32 v[246:247], v[8:9], v[24:25]
	v_pk_add_f32 v[248:249], v[8:9], v[24:25] neg_lo:[0,1] neg_hi:[0,1]
	v_pk_add_f32 v[0:1], v[242:243], v[246:247]
	ds_write_b64 v227, v[0:1] offset:0
	v_pk_add_f32 v[8:9], v[244:245], v[248:249] op_sel:[0,1] op_sel_hi:[1,0] neg_lo:[0,1]
	ds_write_b64 v227, v[8:9] offset:512
	v_pk_add_f32 v[16:17], v[242:243], v[246:247] neg_lo:[0,1] neg_hi:[0,1]
	ds_write_b64 v227, v[16:17] offset:1024
	v_pk_add_f32 v[24:25], v[244:245], v[248:249] op_sel:[0,1] op_sel_hi:[1,0] neg_hi:[0,1]
	ds_write_b64 v227, v[24:25] offset:1536
	v_pk_mul_f32 v[250:251], v[18:19], v[224:225] op_sel:[1,1] op_sel_hi:[1,0] neg_lo:[0,0] neg_hi:[0,0]
	v_pk_fma_f32 v[18:19], v[18:19], v[224:225], v[250:251] op_sel:[0,0,0] op_sel_hi:[0,1,1] neg_lo:[0,0,1] neg_hi:[0,0,0]
	v_pk_mul_f32 v[250:251], v[18:19], v[82:83] op_sel:[1,1] op_sel_hi:[0,1]
	v_pk_fma_f32 v[18:19], v[18:19], v[82:83], v[250:251] op_sel:[0,0,0] op_sel_hi:[1,0,1] neg_hi:[0,0,1]
	v_pk_mul_f32 v[250:251], v[10:11], v[222:223] op_sel:[1,1] op_sel_hi:[1,0] neg_lo:[0,0] neg_hi:[0,0]
	v_pk_fma_f32 v[10:11], v[10:11], v[222:223], v[250:251] op_sel:[0,0,0] op_sel_hi:[0,1,1] neg_lo:[0,0,1] neg_hi:[0,0,0]
	v_pk_mul_f32 v[250:251], v[10:11], v[80:81] op_sel:[1,1] op_sel_hi:[0,1]
	v_pk_fma_f32 v[10:11], v[10:11], v[80:81], v[250:251] op_sel:[0,0,0] op_sel_hi:[1,0,1] neg_hi:[0,0,1]
	v_pk_mul_f32 v[250:251], v[26:27], v[222:223] op_sel:[1,0] op_sel_hi:[1,1] neg_lo:[0,0] neg_hi:[0,0]
	v_pk_fma_f32 v[26:27], v[26:27], v[222:223], v[250:251] op_sel:[0,1,0] op_sel_hi:[0,0,1] neg_lo:[0,0,1] neg_hi:[0,0,0]
	v_pk_mul_f32 v[250:251], v[26:27], v[84:85] op_sel:[1,1] op_sel_hi:[0,1]
	v_pk_fma_f32 v[26:27], v[26:27], v[84:85], v[250:251] op_sel:[0,0,0] op_sel_hi:[1,0,1] neg_hi:[0,0,1]
	v_pk_add_f32 v[242:243], v[2:3], v[18:19]
	v_pk_add_f32 v[244:245], v[2:3], v[18:19] neg_lo:[0,1] neg_hi:[0,1]
	v_pk_add_f32 v[246:247], v[10:11], v[26:27]
	v_pk_add_f32 v[248:249], v[10:11], v[26:27] neg_lo:[0,1] neg_hi:[0,1]
	v_pk_add_f32 v[2:3], v[242:243], v[246:247]
	ds_write_b64 v227, v[2:3] offset:128
	v_pk_add_f32 v[10:11], v[244:245], v[248:249] op_sel:[0,1] op_sel_hi:[1,0] neg_lo:[0,1]
	ds_write_b64 v227, v[10:11] offset:640
	v_pk_add_f32 v[18:19], v[242:243], v[246:247] neg_lo:[0,1] neg_hi:[0,1]
	ds_write_b64 v227, v[18:19] offset:1152
	v_pk_add_f32 v[26:27], v[244:245], v[248:249] op_sel:[0,1] op_sel_hi:[1,0] neg_hi:[0,1]
	ds_write_b64 v227, v[26:27] offset:1664
	v_pk_add_f32 v[20:21], v[20:21], 0 op_sel:[1,0] op_sel_hi:[0,0] neg_lo:[1,0]
	v_pk_mul_f32 v[250:251], v[20:21], v[82:83] op_sel:[1,1] op_sel_hi:[0,1]
	v_pk_fma_f32 v[20:21], v[20:21], v[82:83], v[250:251] op_sel:[0,0,0] op_sel_hi:[1,0,1] neg_hi:[0,0,1]
	v_pk_mul_f32 v[250:251], v[12:13], v[224:225] op_sel:[1,1] op_sel_hi:[1,0] neg_lo:[0,0] neg_hi:[0,0]
	v_pk_fma_f32 v[12:13], v[12:13], v[224:225], v[250:251] op_sel:[0,0,0] op_sel_hi:[0,1,1] neg_lo:[0,0,1] neg_hi:[0,0,0]
	v_pk_mul_f32 v[250:251], v[12:13], v[80:81] op_sel:[1,1] op_sel_hi:[0,1]
	v_pk_fma_f32 v[12:13], v[12:13], v[80:81], v[250:251] op_sel:[0,0,0] op_sel_hi:[1,0,1] neg_hi:[0,0,1]
	v_pk_mul_f32 v[250:251], v[28:29], v[224:225] op_sel:[1,1] op_sel_hi:[1,0] neg_lo:[0,0] neg_hi:[0,1]
	v_pk_fma_f32 v[28:29], v[28:29], v[224:225], v[250:251] op_sel:[0,0,0] op_sel_hi:[0,1,1] neg_lo:[0,1,1] neg_hi:[0,0,0]
	v_pk_mul_f32 v[250:251], v[28:29], v[84:85] op_sel:[1,1] op_sel_hi:[0,1]
	v_pk_fma_f32 v[28:29], v[28:29], v[84:85], v[250:251] op_sel:[0,0,0] op_sel_hi:[1,0,1] neg_hi:[0,0,1]
	v_pk_add_f32 v[242:243], v[4:5], v[20:21]
	v_pk_add_f32 v[244:245], v[4:5], v[20:21] neg_lo:[0,1] neg_hi:[0,1]
	v_pk_add_f32 v[246:247], v[12:13], v[28:29]
	v_pk_add_f32 v[248:249], v[12:13], v[28:29] neg_lo:[0,1] neg_hi:[0,1]
	v_pk_add_f32 v[4:5], v[242:243], v[246:247]
	ds_write_b64 v227, v[4:5] offset:256
	v_pk_add_f32 v[12:13], v[244:245], v[248:249] op_sel:[0,1] op_sel_hi:[1,0] neg_lo:[0,1]
	ds_write_b64 v227, v[12:13] offset:768
; HD float2 cmul(float2 a, float2 b){ return make_float2(a.x*b.x - a.y*b.y, a.x*b.y + a.y*b.x); }
; template<bool INV, bool NOTW>
; HD void bf4c(float2* Z, int i0, int i1, int i2, int i3, float2 w1, float2 w2, float2 w3){
;   float2 a0=Z[i0], a1=Z[i1], a2=Z[i2], a3=Z[i3];
;   if (INV && !NOTW){ a1=cmulc(a1,w1); a2=cmulc(a2,w2); a3=cmulc(a3,w3); }
;   float2 s02=make_float2(a0.x+a2.x,a0.y+a2.y), d02=make_float2(a0.x-a2.x,a0.y-a2.y);
;   float2 s13=make_float2(a1.x+a3.x,a1.y+a3.y), d13=make_float2(a1.x-a3.x,a1.y-a3.y);
;   float2 y0=make_float2(s02.x+s13.x,s02.y+s13.y), y2=make_float2(s02.x-s13.x,s02.y-s13.y);
;   float2 ym=make_float2(d02.x+d13.y,d02.y-d13.x);
;   float2 yp=make_float2(d02.x-d13.y,d02.y+d13.x);
;   float2 y1, y3;
;   if (INV){ y1=yp; y3=ym; } else if (NOTW){ y1=ym; y3=yp; } else { y1=cmul(ym,w1); y2=cmul(y2,w2); y3=cmul(yp,w3); }
;   Z[i0]=y0; Z[i1]=y1; Z[i2]=y2; Z[i3]=y3;
; }
; template<bool INV, int LQ, bool BARRIER=true>
; HD void fft_pass(float2* Z, const float2* twA, const float2* twB, int tid){
;     ...
;   } else if (LQ==10){
;     _Pragma("unroll") for (int e=0;e<2;++e){ int j=tid+512*e; int k=j*tws;
;       float2 w1=cmul(twA[k>>6],twB[k&63]), w2=cmul(w1,w1), w3=cmul(w2,w1);
;       _Pragma("unroll") for (int ip=0;ip<4;++ip){ int base=ip*4096+j; bf4c<INV,false>(Z,base,base+q,base+2*q,base+3*q,w1,w2,w3); } }
;   } else {
;     int j=tid&(q-1); int base0=((tid>>LQ)<<(LQ+2))+j;
;     float2 w1=make_float2(1.f,0.f), w2=w1, w3=w1;
;     if (LQ>0){ int k=j*tws; w1=cmul(twA[k>>6],twB[k&63]); w2=cmul(w1,w1); w3=cmul(w2,w1); }
;     _Pragma("unroll") for (int i=0;i<8;++i){ int base=base0+i*2048; bf4c<INV,(LQ==0)>(Z,base,base+q,base+2*q,base+3*q,w1,w2,w3); }
;   }
;   if (BARRIER) __syncthreads(); else asm volatile("s_waitcnt lgkmcnt(0)" ::: "memory");
; }
; __device__ __forceinline__ void fft_fwd_head(float2* Z, const float2* twA, const float2* twB, int tid){
;   fft_pass<false,10>(Z,twA,twB,tid); fft_pass<false,8>(Z,twA,twB,tid); fft_pass<false,6,false>(Z,twA,twB,tid);
;   fft_pass<false,4,false>(Z,twA,twB,tid); fft_pass<false,2,false>(Z,twA,twB,tid);
; }
; __device__ __forceinline__ void fft_inv_tail(float2* Z, const float2* twA, const float2* twB, int tid){
;   fft_pass<true,2,false>(Z,twA,twB,tid); fft_pass<true,4,false>(Z,twA,twB,tid); fft_pass<true,6>(Z,twA,twB,tid);
;   fft_pass<true,8>(Z,twA,twB,tid); fft_pass<true,10>(Z,twA,twB,tid);
	v_pk_add_f32 v[20:21], v[242:243], v[246:247] neg_lo:[0,1] neg_hi:[0,1]
	ds_write_b64 v227, v[20:21] offset:1280
	v_pk_add_f32 v[28:29], v[244:245], v[248:249] op_sel:[0,1] op_sel_hi:[1,0] neg_hi:[0,1]
	ds_write_b64 v227, v[28:29] offset:1792
	v_pk_mul_f32 v[250:251], v[22:23], v[224:225] op_sel:[1,1] op_sel_hi:[1,0] neg_lo:[0,0] neg_hi:[0,1]
	v_pk_fma_f32 v[22:23], v[22:23], v[224:225], v[250:251] op_sel:[0,0,0] op_sel_hi:[0,1,1] neg_lo:[0,1,1] neg_hi:[0,0,0]
	v_pk_mul_f32 v[250:251], v[22:23], v[82:83] op_sel:[1,1] op_sel_hi:[0,1]
	v_pk_fma_f32 v[22:23], v[22:23], v[82:83], v[250:251] op_sel:[0,0,0] op_sel_hi:[1,0,1] neg_hi:[0,0,1]
	v_pk_mul_f32 v[250:251], v[14:15], v[222:223] op_sel:[1,0] op_sel_hi:[1,1] neg_lo:[0,0] neg_hi:[0,0]
	v_pk_fma_f32 v[14:15], v[14:15], v[222:223], v[250:251] op_sel:[0,1,0] op_sel_hi:[0,0,1] neg_lo:[0,0,1] neg_hi:[0,0,0]
	v_pk_mul_f32 v[250:251], v[14:15], v[80:81] op_sel:[1,1] op_sel_hi:[0,1]
	v_pk_fma_f32 v[14:15], v[14:15], v[80:81], v[250:251] op_sel:[0,0,0] op_sel_hi:[1,0,1] neg_hi:[0,0,1]
	v_pk_mul_f32 v[250:251], v[30:31], v[222:223] op_sel:[1,1] op_sel_hi:[1,0] neg_lo:[0,1] neg_hi:[0,1]
	v_pk_fma_f32 v[30:31], v[30:31], v[222:223], v[250:251] op_sel:[0,0,0] op_sel_hi:[0,1,1] neg_lo:[0,1,1] neg_hi:[0,1,0]
	v_pk_mul_f32 v[250:251], v[30:31], v[84:85] op_sel:[1,1] op_sel_hi:[0,1]
	v_pk_fma_f32 v[30:31], v[30:31], v[84:85], v[250:251] op_sel:[0,0,0] op_sel_hi:[1,0,1] neg_hi:[0,0,1]
	v_pk_add_f32 v[242:243], v[6:7], v[22:23]
	v_pk_add_f32 v[244:245], v[6:7], v[22:23] neg_lo:[0,1] neg_hi:[0,1]
	v_pk_add_f32 v[246:247], v[14:15], v[30:31]
	v_pk_add_f32 v[248:249], v[14:15], v[30:31] neg_lo:[0,1] neg_hi:[0,1]
	v_pk_add_f32 v[6:7], v[242:243], v[246:247]
	ds_write_b64 v227, v[6:7] offset:384
	v_pk_add_f32 v[14:15], v[244:245], v[248:249] op_sel:[0,1] op_sel_hi:[1,0] neg_lo:[0,1]
	ds_write_b64 v227, v[14:15] offset:896
	v_pk_add_f32 v[22:23], v[242:243], v[246:247] neg_lo:[0,1] neg_hi:[0,1]
	ds_write_b64 v227, v[22:23] offset:1408
	v_pk_add_f32 v[30:31], v[244:245], v[248:249] op_sel:[0,1] op_sel_hi:[1,0] neg_hi:[0,1]
	ds_write_b64 v227, v[30:31] offset:1920
	s_waitcnt lgkmcnt(0)
	s_barrier
	v_and_b32_e32 v8, 255, v154
	v_lshrrev_b32_e32 v9, 4, v8
	v_lshlrev_b32_e32 v9, 3, v9
	v_add_u32_e32 v9, 0x20800, v9
	v_and_b32_e32 v10, 15, v8
	v_lshlrev_b32_e32 v10, 5, v10
	v_add_u32_e32 v10, 0x20a00, v10
	ds_read_b64 v[0:1], v9
	ds_read_b64 v[2:3], v10
	s_waitcnt lgkmcnt(0)
	v_pk_mul_f32 v[250:251], v[0:1], v[2:3] op_sel:[1,1] op_sel_hi:[1,0]
	v_pk_fma_f32 v[80:81], v[0:1], v[2:3], v[250:251] op_sel:[0,0,0] op_sel_hi:[0,1,1] neg_lo:[0,0,1]
	v_pk_mul_f32 v[250:251], v[80:81], v[80:81] op_sel:[1,1] op_sel_hi:[1,0]
	v_pk_fma_f32 v[82:83], v[80:81], v[80:81], v[250:251] op_sel:[0,0,0] op_sel_hi:[0,1,1] neg_lo:[0,0,1]
	v_pk_mul_f32 v[250:251], v[82:83], v[80:81] op_sel:[1,1] op_sel_hi:[1,0]
	v_pk_fma_f32 v[84:85], v[82:83], v[80:81], v[250:251] op_sel:[0,0,0] op_sel_hi:[0,1,1] neg_lo:[0,0,1]
	v_lshrrev_b32_e32 v9, 2, v8
	v_lshlrev_b32_e32 v9, 3, v9
	v_add_u32_e32 v9, 0x20800, v9
	v_and_b32_e32 v10, 3, v8
	v_lshlrev_b32_e32 v10, 7, v10
	v_add_u32_e32 v10, 0x20a00, v10
	ds_read_b64 v[0:1], v9
	ds_read_b64 v[2:3], v10
	s_waitcnt lgkmcnt(0)
	v_pk_mul_f32 v[250:251], v[0:1], v[2:3] op_sel:[1,1] op_sel_hi:[1,0]
	v_pk_fma_f32 v[236:237], v[0:1], v[2:3], v[250:251] op_sel:[0,0,0] op_sel_hi:[0,1,1] neg_lo:[0,0,1]
	v_pk_mul_f32 v[250:251], v[236:237], v[236:237] op_sel:[1,1] op_sel_hi:[1,0]
	v_pk_fma_f32 v[238:239], v[236:237], v[236:237], v[250:251] op_sel:[0,0,0] op_sel_hi:[0,1,1] neg_lo:[0,0,1]
	v_pk_mul_f32 v[250:251], v[238:239], v[236:237] op_sel:[1,1] op_sel_hi:[1,0]
	v_pk_fma_f32 v[240:241], v[238:239], v[236:237], v[250:251] op_sel:[0,0,0] op_sel_hi:[0,1,1] neg_lo:[0,0,1]
	v_lshrrev_b32_e32 v226, 8, v154
	v_lshlrev_b32_e32 v226, 12, v226
	v_and_b32_e32 v227, 255, v154
	v_add_u32_e32 v226, v226, v227
	v_lshlrev_b32_e32 v226, 3, v226
	v_add_u32_e32 v227, 0x10000, v226
	ds_read_b64 v[0:1], v226 offset:0
	ds_read_b64 v[2:3], v226 offset:2048
	ds_read_b64 v[4:5], v226 offset:4096
	ds_read_b64 v[6:7], v226 offset:6144
	ds_read_b64 v[8:9], v226 offset:8192
	ds_read_b64 v[10:11], v226 offset:10240
	ds_read_b64 v[12:13], v226 offset:12288
	ds_read_b64 v[14:15], v226 offset:14336
	ds_read_b64 v[16:17], v226 offset:16384
	ds_read_b64 v[18:19], v226 offset:18432
	ds_read_b64 v[20:21], v226 offset:20480
	ds_read_b64 v[22:23], v226 offset:22528
	ds_read_b64 v[24:25], v226 offset:24576
	ds_read_b64 v[26:27], v226 offset:26624
	ds_read_b64 v[28:29], v226 offset:28672
	ds_read_b64 v[30:31], v226 offset:30720
	s_waitcnt lgkmcnt(12)
	v_pk_mul_f32 v[250:251], v[4:5], v[238:239] op_sel:[1,1] op_sel_hi:[0,1]
	v_pk_fma_f32 v[4:5], v[4:5], v[238:239], v[250:251] op_sel:[0,0,0] op_sel_hi:[1,0,1] neg_hi:[0,0,1]
	v_pk_mul_f32 v[250:251], v[2:3], v[236:237] op_sel:[1,1] op_sel_hi:[0,1]
	v_pk_fma_f32 v[2:3], v[2:3], v[236:237], v[250:251] op_sel:[0,0,0] op_sel_hi:[1,0,1] neg_hi:[0,0,1]
	v_pk_mul_f32 v[250:251], v[6:7], v[240:241] op_sel:[1,1] op_sel_hi:[0,1]
	v_pk_fma_f32 v[6:7], v[6:7], v[240:241], v[250:251] op_sel:[0,0,0] op_sel_hi:[1,0,1] neg_hi:[0,0,1]
	v_pk_add_f32 v[242:243], v[0:1], v[4:5]
	v_pk_add_f32 v[244:245], v[0:1], v[4:5] neg_lo:[0,1] neg_hi:[0,1]
	v_pk_add_f32 v[246:247], v[2:3], v[6:7]
	v_pk_add_f32 v[248:249], v[2:3], v[6:7] neg_lo:[0,1] neg_hi:[0,1]
	v_pk_add_f32 v[0:1], v[242:243], v[246:247]
	v_pk_add_f32 v[2:3], v[244:245], v[248:249] op_sel:[0,1] op_sel_hi:[1,0] neg_lo:[0,1]
	v_pk_add_f32 v[4:5], v[242:243], v[246:247] neg_lo:[0,1] neg_hi:[0,1]
	v_pk_add_f32 v[6:7], v[244:245], v[248:249] op_sel:[0,1] op_sel_hi:[1,0] neg_hi:[0,1]
	s_waitcnt lgkmcnt(8)
; HD float2 cmul(float2 a, float2 b){ return make_float2(a.x*b.x - a.y*b.y, a.x*b.y + a.y*b.x); }
; template<bool INV, bool NOTW>
; HD void bf4c(float2* Z, int i0, int i1, int i2, int i3, float2 w1, float2 w2, float2 w3){
;   float2 a0=Z[i0], a1=Z[i1], a2=Z[i2], a3=Z[i3];
;   if (INV && !NOTW){ a1=cmulc(a1,w1); a2=cmulc(a2,w2); a3=cmulc(a3,w3); }
;   float2 s02=make_float2(a0.x+a2.x,a0.y+a2.y), d02=make_float2(a0.x-a2.x,a0.y-a2.y);
;   float2 s13=make_float2(a1.x+a3.x,a1.y+a3.y), d13=make_float2(a1.x-a3.x,a1.y-a3.y);
;   float2 y0=make_float2(s02.x+s13.x,s02.y+s13.y), y2=make_float2(s02.x-s13.x,s02.y-s13.y);
;   float2 ym=make_float2(d02.x+d13.y,d02.y-d13.x);
;   float2 yp=make_float2(d02.x-d13.y,d02.y+d13.x);
;   float2 y1, y3;
;   if (INV){ y1=yp; y3=ym; } else if (NOTW){ y1=ym; y3=yp; } else { y1=cmul(ym,w1); y2=cmul(y2,w2); y3=cmul(yp,w3); }
;   Z[i0]=y0; Z[i1]=y1; Z[i2]=y2; Z[i3]=y3;
; }
; template<bool INV, int LQ, bool BARRIER=true>
; HD void fft_pass(float2* Z, const float2* twA, const float2* twB, int tid){
;     ...
;   } else if (LQ==10){
;     _Pragma("unroll") for (int e=0;e<2;++e){ int j=tid+512*e; int k=j*tws;
;       float2 w1=cmul(twA[k>>6],twB[k&63]), w2=cmul(w1,w1), w3=cmul(w2,w1);
;       _Pragma("unroll") for (int ip=0;ip<4;++ip){ int base=ip*4096+j; bf4c<INV,false>(Z,base,base+q,base+2*q,base+3*q,w1,w2,w3); } }
;   } else {
;     int j=tid&(q-1); int base0=((tid>>LQ)<<(LQ+2))+j;
;     float2 w1=make_float2(1.f,0.f), w2=w1, w3=w1;
;     if (LQ>0){ int k=j*tws; w1=cmul(twA[k>>6],twB[k&63]); w2=cmul(w1,w1); w3=cmul(w2,w1); }
;     _Pragma("unroll") for (int i=0;i<8;++i){ int base=base0+i*2048; bf4c<INV,(LQ==0)>(Z,base,base+q,base+2*q,base+3*q,w1,w2,w3); }
;   }
;   if (BARRIER) __syncthreads(); else asm volatile("s_waitcnt lgkmcnt(0)" ::: "memory");
; }
; __device__ __forceinline__ void fft_fwd_head(float2* Z, const float2* twA, const float2* twB, int tid){
;   fft_pass<false,10>(Z,twA,twB,tid); fft_pass<false,8>(Z,twA,twB,tid); fft_pass<false,6,false>(Z,twA,twB,tid);
;   fft_pass<false,4,false>(Z,twA,twB,tid); fft_pass<false,2,false>(Z,twA,twB,tid);
; }
; __device__ __forceinline__ void fft_inv_tail(float2* Z, const float2* twA, const float2* twB, int tid){
;   fft_pass<true,2,false>(Z,twA,twB,tid); fft_pass<true,4,false>(Z,twA,twB,tid); fft_pass<true,6>(Z,twA,twB,tid);
;   fft_pass<true,8>(Z,twA,twB,tid); fft_pass<true,10>(Z,twA,twB,tid);
	v_pk_mul_f32 v[250:251], v[12:13], v[238:239] op_sel:[1,1] op_sel_hi:[0,1]
	v_pk_fma_f32 v[12:13], v[12:13], v[238:239], v[250:251] op_sel:[0,0,0] op_sel_hi:[1,0,1] neg_hi:[0,0,1]
	v_pk_mul_f32 v[250:251], v[10:11], v[236:237] op_sel:[1,1] op_sel_hi:[0,1]
	v_pk_fma_f32 v[10:11], v[10:11], v[236:237], v[250:251] op_sel:[0,0,0] op_sel_hi:[1,0,1] neg_hi:[0,0,1]
	v_pk_mul_f32 v[250:251], v[14:15], v[240:241] op_sel:[1,1] op_sel_hi:[0,1]
	v_pk_fma_f32 v[14:15], v[14:15], v[240:241], v[250:251] op_sel:[0,0,0] op_sel_hi:[1,0,1] neg_hi:[0,0,1]
	v_pk_add_f32 v[242:243], v[8:9], v[12:13]
	v_pk_add_f32 v[244:245], v[8:9], v[12:13] neg_lo:[0,1] neg_hi:[0,1]
	v_pk_add_f32 v[246:247], v[10:11], v[14:15]
	v_pk_add_f32 v[248:249], v[10:11], v[14:15] neg_lo:[0,1] neg_hi:[0,1]
	v_pk_add_f32 v[8:9], v[242:243], v[246:247]
	v_pk_add_f32 v[10:11], v[244:245], v[248:249] op_sel:[0,1] op_sel_hi:[1,0] neg_lo:[0,1]
	v_pk_add_f32 v[12:13], v[242:243], v[246:247] neg_lo:[0,1] neg_hi:[0,1]
	v_pk_add_f32 v[14:15], v[244:245], v[248:249] op_sel:[0,1] op_sel_hi:[1,0] neg_hi:[0,1]
	s_waitcnt lgkmcnt(4)
	v_pk_mul_f32 v[250:251], v[20:21], v[238:239] op_sel:[1,1] op_sel_hi:[0,1]
	v_pk_fma_f32 v[20:21], v[20:21], v[238:239], v[250:251] op_sel:[0,0,0] op_sel_hi:[1,0,1] neg_hi:[0,0,1]
	v_pk_mul_f32 v[250:251], v[18:19], v[236:237] op_sel:[1,1] op_sel_hi:[0,1]
	v_pk_fma_f32 v[18:19], v[18:19], v[236:237], v[250:251] op_sel:[0,0,0] op_sel_hi:[1,0,1] neg_hi:[0,0,1]
	v_pk_mul_f32 v[250:251], v[22:23], v[240:241] op_sel:[1,1] op_sel_hi:[0,1]
	v_pk_fma_f32 v[22:23], v[22:23], v[240:241], v[250:251] op_sel:[0,0,0] op_sel_hi:[1,0,1] neg_hi:[0,0,1]
	v_pk_add_f32 v[242:243], v[16:17], v[20:21]
	v_pk_add_f32 v[244:245], v[16:17], v[20:21] neg_lo:[0,1] neg_hi:[0,1]
	v_pk_add_f32 v[246:247], v[18:19], v[22:23]
	v_pk_add_f32 v[248:249], v[18:19], v[22:23] neg_lo:[0,1] neg_hi:[0,1]
	v_pk_add_f32 v[16:17], v[242:243], v[246:247]
	v_pk_add_f32 v[18:19], v[244:245], v[248:249] op_sel:[0,1] op_sel_hi:[1,0] neg_lo:[0,1]
	v_pk_add_f32 v[20:21], v[242:243], v[246:247] neg_lo:[0,1] neg_hi:[0,1]
	v_pk_add_f32 v[22:23], v[244:245], v[248:249] op_sel:[0,1] op_sel_hi:[1,0] neg_hi:[0,1]
	s_waitcnt lgkmcnt(0)
	v_pk_mul_f32 v[250:251], v[28:29], v[238:239] op_sel:[1,1] op_sel_hi:[0,1]
	v_pk_fma_f32 v[28:29], v[28:29], v[238:239], v[250:251] op_sel:[0,0,0] op_sel_hi:[1,0,1] neg_hi:[0,0,1]
	v_pk_mul_f32 v[250:251], v[26:27], v[236:237] op_sel:[1,1] op_sel_hi:[0,1]
	v_pk_fma_f32 v[26:27], v[26:27], v[236:237], v[250:251] op_sel:[0,0,0] op_sel_hi:[1,0,1] neg_hi:[0,0,1]
	v_pk_mul_f32 v[250:251], v[30:31], v[240:241] op_sel:[1,1] op_sel_hi:[0,1]
	v_pk_fma_f32 v[30:31], v[30:31], v[240:241], v[250:251] op_sel:[0,0,0] op_sel_hi:[1,0,1] neg_hi:[0,0,1]
	v_pk_add_f32 v[242:243], v[24:25], v[28:29]
	v_pk_add_f32 v[244:245], v[24:25], v[28:29] neg_lo:[0,1] neg_hi:[0,1]
	v_pk_add_f32 v[246:247], v[26:27], v[30:31]
	v_pk_add_f32 v[248:249], v[26:27], v[30:31] neg_lo:[0,1] neg_hi:[0,1]
	v_pk_add_f32 v[24:25], v[242:243], v[246:247]
	v_pk_add_f32 v[26:27], v[244:245], v[248:249] op_sel:[0,1] op_sel_hi:[1,0] neg_lo:[0,1]
	v_pk_add_f32 v[28:29], v[242:243], v[246:247] neg_lo:[0,1] neg_hi:[0,1]
	v_pk_add_f32 v[30:31], v[244:245], v[248:249] op_sel:[0,1] op_sel_hi:[1,0] neg_hi:[0,1]
	v_pk_mul_f32 v[250:251], v[16:17], v[82:83] op_sel:[1,1] op_sel_hi:[0,1]
	v_pk_fma_f32 v[16:17], v[16:17], v[82:83], v[250:251] op_sel:[0,0,0] op_sel_hi:[1,0,1] neg_hi:[0,0,1]
	v_pk_mul_f32 v[250:251], v[8:9], v[80:81] op_sel:[1,1] op_sel_hi:[0,1]
	v_pk_fma_f32 v[8:9], v[8:9], v[80:81], v[250:251] op_sel:[0,0,0] op_sel_hi:[1,0,1] neg_hi:[0,0,1]
	v_pk_mul_f32 v[250:251], v[24:25], v[84:85] op_sel:[1,1] op_sel_hi:[0,1]
	v_pk_fma_f32 v[24:25], v[24:25], v[84:85], v[250:251] op_sel:[0,0,0] op_sel_hi:[1,0,1] neg_hi:[0,0,1]
	v_pk_add_f32 v[242:243], v[0:1], v[16:17]
	v_pk_add_f32 v[244:245], v[0:1], v[16:17] neg_lo:[0,1] neg_hi:[0,1]
	v_pk_add_f32 v[246:247], v[8:9], v[24:25]
	v_pk_add_f32 v[248:249], v[8:9], v[24:25] neg_lo:[0,1] neg_hi:[0,1]
	v_pk_add_f32 v[0:1], v[242:243], v[246:247]
	ds_write_b64 v226, v[0:1] offset:0
	v_pk_add_f32 v[8:9], v[244:245], v[248:249] op_sel:[0,1] op_sel_hi:[1,0] neg_lo:[0,1]
	ds_write_b64 v226, v[8:9] offset:8192
	v_pk_add_f32 v[16:17], v[242:243], v[246:247] neg_lo:[0,1] neg_hi:[0,1]
	ds_write_b64 v226, v[16:17] offset:16384
	v_pk_add_f32 v[24:25], v[244:245], v[248:249] op_sel:[0,1] op_sel_hi:[1,0] neg_hi:[0,1]
	ds_write_b64 v226, v[24:25] offset:24576
	v_pk_mul_f32 v[250:251], v[18:19], v[224:225] op_sel:[1,1] op_sel_hi:[1,0] neg_lo:[0,0] neg_hi:[0,0]
	v_pk_fma_f32 v[18:19], v[18:19], v[224:225], v[250:251] op_sel:[0,0,0] op_sel_hi:[0,1,1] neg_lo:[0,0,1] neg_hi:[0,0,0]
	v_pk_mul_f32 v[250:251], v[18:19], v[82:83] op_sel:[1,1] op_sel_hi:[0,1]
	v_pk_fma_f32 v[18:19], v[18:19], v[82:83], v[250:251] op_sel:[0,0,0] op_sel_hi:[1,0,1] neg_hi:[0,0,1]
	v_pk_mul_f32 v[250:251], v[10:11], v[222:223] op_sel:[1,1] op_sel_hi:[1,0] neg_lo:[0,0] neg_hi:[0,0]
	v_pk_fma_f32 v[10:11], v[10:11], v[222:223], v[250:251] op_sel:[0,0,0] op_sel_hi:[0,1,1] neg_lo:[0,0,1] neg_hi:[0,0,0]
	v_pk_mul_f32 v[250:251], v[10:11], v[80:81] op_sel:[1,1] op_sel_hi:[0,1]
	v_pk_fma_f32 v[10:11], v[10:11], v[80:81], v[250:251] op_sel:[0,0,0] op_sel_hi:[1,0,1] neg_hi:[0,0,1]
	v_pk_mul_f32 v[250:251], v[26:27], v[222:223] op_sel:[1,0] op_sel_hi:[1,1] neg_lo:[0,0] neg_hi:[0,0]
	v_pk_fma_f32 v[26:27], v[26:27], v[222:223], v[250:251] op_sel:[0,1,0] op_sel_hi:[0,0,1] neg_lo:[0,0,1] neg_hi:[0,0,0]
	v_pk_mul_f32 v[250:251], v[26:27], v[84:85] op_sel:[1,1] op_sel_hi:[0,1]
	v_pk_fma_f32 v[26:27], v[26:27], v[84:85], v[250:251] op_sel:[0,0,0] op_sel_hi:[1,0,1] neg_hi:[0,0,1]
; HD float2 cmul(float2 a, float2 b){ return make_float2(a.x*b.x - a.y*b.y, a.x*b.y + a.y*b.x); }
; template<bool INV, bool NOTW>
; HD void bf4c(float2* Z, int i0, int i1, int i2, int i3, float2 w1, float2 w2, float2 w3){
;   float2 a0=Z[i0], a1=Z[i1], a2=Z[i2], a3=Z[i3];
;   if (INV && !NOTW){ a1=cmulc(a1,w1); a2=cmulc(a2,w2); a3=cmulc(a3,w3); }
;   float2 s02=make_float2(a0.x+a2.x,a0.y+a2.y), d02=make_float2(a0.x-a2.x,a0.y-a2.y);
;   float2 s13=make_float2(a1.x+a3.x,a1.y+a3.y), d13=make_float2(a1.x-a3.x,a1.y-a3.y);
;   float2 y0=make_float2(s02.x+s13.x,s02.y+s13.y), y2=make_float2(s02.x-s13.x,s02.y-s13.y);
;   float2 ym=make_float2(d02.x+d13.y,d02.y-d13.x);
;   float2 yp=make_float2(d02.x-d13.y,d02.y+d13.x);
;   float2 y1, y3;
;   if (INV){ y1=yp; y3=ym; } else if (NOTW){ y1=ym; y3=yp; } else { y1=cmul(ym,w1); y2=cmul(y2,w2); y3=cmul(yp,w3); }
;   Z[i0]=y0; Z[i1]=y1; Z[i2]=y2; Z[i3]=y3;
; }
; template<bool INV, int LQ, bool BARRIER=true>
; HD void fft_pass(float2* Z, const float2* twA, const float2* twB, int tid){
;     ...
;   } else if (LQ==10){
;     _Pragma("unroll") for (int e=0;e<2;++e){ int j=tid+512*e; int k=j*tws;
;       float2 w1=cmul(twA[k>>6],twB[k&63]), w2=cmul(w1,w1), w3=cmul(w2,w1);
;       _Pragma("unroll") for (int ip=0;ip<4;++ip){ int base=ip*4096+j; bf4c<INV,false>(Z,base,base+q,base+2*q,base+3*q,w1,w2,w3); } }
;   } else {
;     int j=tid&(q-1); int base0=((tid>>LQ)<<(LQ+2))+j;
;     float2 w1=make_float2(1.f,0.f), w2=w1, w3=w1;
;     if (LQ>0){ int k=j*tws; w1=cmul(twA[k>>6],twB[k&63]); w2=cmul(w1,w1); w3=cmul(w2,w1); }
;     _Pragma("unroll") for (int i=0;i<8;++i){ int base=base0+i*2048; bf4c<INV,(LQ==0)>(Z,base,base+q,base+2*q,base+3*q,w1,w2,w3); }
;   }
;   if (BARRIER) __syncthreads(); else asm volatile("s_waitcnt lgkmcnt(0)" ::: "memory");
; }
; __device__ __forceinline__ void fft_fwd_head(float2* Z, const float2* twA, const float2* twB, int tid){
;   fft_pass<false,10>(Z,twA,twB,tid); fft_pass<false,8>(Z,twA,twB,tid); fft_pass<false,6,false>(Z,twA,twB,tid);
;   fft_pass<false,4,false>(Z,twA,twB,tid); fft_pass<false,2,false>(Z,twA,twB,tid);
; }
; __device__ __forceinline__ void fft_inv_tail(float2* Z, const float2* twA, const float2* twB, int tid){
;   fft_pass<true,2,false>(Z,twA,twB,tid); fft_pass<true,4,false>(Z,twA,twB,tid); fft_pass<true,6>(Z,twA,twB,tid);
;   fft_pass<true,8>(Z,twA,twB,tid); fft_pass<true,10>(Z,twA,twB,tid);
	v_pk_add_f32 v[242:243], v[2:3], v[18:19]
	v_pk_add_f32 v[244:245], v[2:3], v[18:19] neg_lo:[0,1] neg_hi:[0,1]
	v_pk_add_f32 v[246:247], v[10:11], v[26:27]
	v_pk_add_f32 v[248:249], v[10:11], v[26:27] neg_lo:[0,1] neg_hi:[0,1]
	v_pk_add_f32 v[2:3], v[242:243], v[246:247]
	ds_write_b64 v226, v[2:3] offset:2048
	v_pk_add_f32 v[10:11], v[244:245], v[248:249] op_sel:[0,1] op_sel_hi:[1,0] neg_lo:[0,1]
	ds_write_b64 v226, v[10:11] offset:10240
	v_pk_add_f32 v[18:19], v[242:243], v[246:247] neg_lo:[0,1] neg_hi:[0,1]
	ds_write_b64 v226, v[18:19] offset:18432
	v_pk_add_f32 v[26:27], v[244:245], v[248:249] op_sel:[0,1] op_sel_hi:[1,0] neg_hi:[0,1]
	ds_write_b64 v226, v[26:27] offset:26624
	v_pk_add_f32 v[20:21], v[20:21], 0 op_sel:[1,0] op_sel_hi:[0,0] neg_lo:[1,0]
	v_pk_mul_f32 v[250:251], v[20:21], v[82:83] op_sel:[1,1] op_sel_hi:[0,1]
	v_pk_fma_f32 v[20:21], v[20:21], v[82:83], v[250:251] op_sel:[0,0,0] op_sel_hi:[1,0,1] neg_hi:[0,0,1]
	v_pk_mul_f32 v[250:251], v[12:13], v[224:225] op_sel:[1,1] op_sel_hi:[1,0] neg_lo:[0,0] neg_hi:[0,0]
	v_pk_fma_f32 v[12:13], v[12:13], v[224:225], v[250:251] op_sel:[0,0,0] op_sel_hi:[0,1,1] neg_lo:[0,0,1] neg_hi:[0,0,0]
	v_pk_mul_f32 v[250:251], v[12:13], v[80:81] op_sel:[1,1] op_sel_hi:[0,1]
	v_pk_fma_f32 v[12:13], v[12:13], v[80:81], v[250:251] op_sel:[0,0,0] op_sel_hi:[1,0,1] neg_hi:[0,0,1]
	v_pk_mul_f32 v[250:251], v[28:29], v[224:225] op_sel:[1,1] op_sel_hi:[1,0] neg_lo:[0,0] neg_hi:[0,1]
	v_pk_fma_f32 v[28:29], v[28:29], v[224:225], v[250:251] op_sel:[0,0,0] op_sel_hi:[0,1,1] neg_lo:[0,1,1] neg_hi:[0,0,0]
	v_pk_mul_f32 v[250:251], v[28:29], v[84:85] op_sel:[1,1] op_sel_hi:[0,1]
	v_pk_fma_f32 v[28:29], v[28:29], v[84:85], v[250:251] op_sel:[0,0,0] op_sel_hi:[1,0,1] neg_hi:[0,0,1]
	v_pk_add_f32 v[242:243], v[4:5], v[20:21]
	v_pk_add_f32 v[244:245], v[4:5], v[20:21] neg_lo:[0,1] neg_hi:[0,1]
	v_pk_add_f32 v[246:247], v[12:13], v[28:29]
	v_pk_add_f32 v[248:249], v[12:13], v[28:29] neg_lo:[0,1] neg_hi:[0,1]
	v_pk_add_f32 v[4:5], v[242:243], v[246:247]
	ds_write_b64 v226, v[4:5] offset:4096
	v_pk_add_f32 v[12:13], v[244:245], v[248:249] op_sel:[0,1] op_sel_hi:[1,0] neg_lo:[0,1]
	ds_write_b64 v226, v[12:13] offset:12288
	v_pk_add_f32 v[20:21], v[242:243], v[246:247] neg_lo:[0,1] neg_hi:[0,1]
	ds_write_b64 v226, v[20:21] offset:20480
	v_pk_add_f32 v[28:29], v[244:245], v[248:249] op_sel:[0,1] op_sel_hi:[1,0] neg_hi:[0,1]
	ds_write_b64 v226, v[28:29] offset:28672
	v_pk_mul_f32 v[250:251], v[22:23], v[224:225] op_sel:[1,1] op_sel_hi:[1,0] neg_lo:[0,0] neg_hi:[0,1]
	v_pk_fma_f32 v[22:23], v[22:23], v[224:225], v[250:251] op_sel:[0,0,0] op_sel_hi:[0,1,1] neg_lo:[0,1,1] neg_hi:[0,0,0]
	v_pk_mul_f32 v[250:251], v[22:23], v[82:83] op_sel:[1,1] op_sel_hi:[0,1]
	v_pk_fma_f32 v[22:23], v[22:23], v[82:83], v[250:251] op_sel:[0,0,0] op_sel_hi:[1,0,1] neg_hi:[0,0,1]
	v_pk_mul_f32 v[250:251], v[14:15], v[222:223] op_sel:[1,0] op_sel_hi:[1,1] neg_lo:[0,0] neg_hi:[0,0]
	v_pk_fma_f32 v[14:15], v[14:15], v[222:223], v[250:251] op_sel:[0,1,0] op_sel_hi:[0,0,1] neg_lo:[0,0,1] neg_hi:[0,0,0]
	v_pk_mul_f32 v[250:251], v[14:15], v[80:81] op_sel:[1,1] op_sel_hi:[0,1]
	v_pk_fma_f32 v[14:15], v[14:15], v[80:81], v[250:251] op_sel:[0,0,0] op_sel_hi:[1,0,1] neg_hi:[0,0,1]
	v_pk_mul_f32 v[250:251], v[30:31], v[222:223] op_sel:[1,1] op_sel_hi:[1,0] neg_lo:[0,1] neg_hi:[0,1]
	v_pk_fma_f32 v[30:31], v[30:31], v[222:223], v[250:251] op_sel:[0,0,0] op_sel_hi:[0,1,1] neg_lo:[0,1,1] neg_hi:[0,1,0]
	v_pk_mul_f32 v[250:251], v[30:31], v[84:85] op_sel:[1,1] op_sel_hi:[0,1]
	v_pk_fma_f32 v[30:31], v[30:31], v[84:85], v[250:251] op_sel:[0,0,0] op_sel_hi:[1,0,1] neg_hi:[0,0,1]
	v_pk_add_f32 v[242:243], v[6:7], v[22:23]
	v_pk_add_f32 v[244:245], v[6:7], v[22:23] neg_lo:[0,1] neg_hi:[0,1]
	v_pk_add_f32 v[246:247], v[14:15], v[30:31]
	v_pk_add_f32 v[248:249], v[14:15], v[30:31] neg_lo:[0,1] neg_hi:[0,1]
	v_pk_add_f32 v[6:7], v[242:243], v[246:247]
	ds_write_b64 v226, v[6:7] offset:6144
	v_pk_add_f32 v[14:15], v[244:245], v[248:249] op_sel:[0,1] op_sel_hi:[1,0] neg_lo:[0,1]
	ds_write_b64 v226, v[14:15] offset:14336
	v_pk_add_f32 v[22:23], v[242:243], v[246:247] neg_lo:[0,1] neg_hi:[0,1]
	ds_write_b64 v226, v[22:23] offset:22528
	v_pk_add_f32 v[30:31], v[244:245], v[248:249] op_sel:[0,1] op_sel_hi:[1,0] neg_hi:[0,1]
	ds_write_b64 v226, v[30:31] offset:30720
	ds_read_b64 v[0:1], v227 offset:0
	ds_read_b64 v[2:3], v227 offset:2048
	ds_read_b64 v[4:5], v227 offset:4096
	ds_read_b64 v[6:7], v227 offset:6144
	ds_read_b64 v[8:9], v227 offset:8192
	ds_read_b64 v[10:11], v227 offset:10240
	ds_read_b64 v[12:13], v227 offset:12288
	ds_read_b64 v[14:15], v227 offset:14336
	ds_read_b64 v[16:17], v227 offset:16384
	ds_read_b64 v[18:19], v227 offset:18432
	ds_read_b64 v[20:21], v227 offset:20480
	ds_read_b64 v[22:23], v227 offset:22528
	ds_read_b64 v[24:25], v227 offset:24576
	ds_read_b64 v[26:27], v227 offset:26624
	ds_read_b64 v[28:29], v227 offset:28672
	ds_read_b64 v[30:31], v227 offset:30720
	s_waitcnt lgkmcnt(12)
	v_pk_mul_f32 v[250:251], v[4:5], v[238:239] op_sel:[1,1] op_sel_hi:[0,1]
	v_pk_fma_f32 v[4:5], v[4:5], v[238:239], v[250:251] op_sel:[0,0,0] op_sel_hi:[1,0,1] neg_hi:[0,0,1]
	v_pk_mul_f32 v[250:251], v[2:3], v[236:237] op_sel:[1,1] op_sel_hi:[0,1]
	v_pk_fma_f32 v[2:3], v[2:3], v[236:237], v[250:251] op_sel:[0,0,0] op_sel_hi:[1,0,1] neg_hi:[0,0,1]
	v_pk_mul_f32 v[250:251], v[6:7], v[240:241] op_sel:[1,1] op_sel_hi:[0,1]
	v_pk_fma_f32 v[6:7], v[6:7], v[240:241], v[250:251] op_sel:[0,0,0] op_sel_hi:[1,0,1] neg_hi:[0,0,1]
	v_pk_add_f32 v[242:243], v[0:1], v[4:5]
	v_pk_add_f32 v[244:245], v[0:1], v[4:5] neg_lo:[0,1] neg_hi:[0,1]
	v_pk_add_f32 v[246:247], v[2:3], v[6:7]
	v_pk_add_f32 v[248:249], v[2:3], v[6:7] neg_lo:[0,1] neg_hi:[0,1]
	v_pk_add_f32 v[0:1], v[242:243], v[246:247]
	v_pk_add_f32 v[2:3], v[244:245], v[248:249] op_sel:[0,1] op_sel_hi:[1,0] neg_lo:[0,1]
	v_pk_add_f32 v[4:5], v[242:243], v[246:247] neg_lo:[0,1] neg_hi:[0,1]
	v_pk_add_f32 v[6:7], v[244:245], v[248:249] op_sel:[0,1] op_sel_hi:[1,0] neg_hi:[0,1]
	s_waitcnt lgkmcnt(8)
; HD float2 cmul(float2 a, float2 b){ return make_float2(a.x*b.x - a.y*b.y, a.x*b.y + a.y*b.x); }
; template<bool INV, bool NOTW>
; HD void bf4c(float2* Z, int i0, int i1, int i2, int i3, float2 w1, float2 w2, float2 w3){
;   float2 a0=Z[i0], a1=Z[i1], a2=Z[i2], a3=Z[i3];
;   if (INV && !NOTW){ a1=cmulc(a1,w1); a2=cmulc(a2,w2); a3=cmulc(a3,w3); }
;   float2 s02=make_float2(a0.x+a2.x,a0.y+a2.y), d02=make_float2(a0.x-a2.x,a0.y-a2.y);
;   float2 s13=make_float2(a1.x+a3.x,a1.y+a3.y), d13=make_float2(a1.x-a3.x,a1.y-a3.y);
;   float2 y0=make_float2(s02.x+s13.x,s02.y+s13.y), y2=make_float2(s02.x-s13.x,s02.y-s13.y);
;   float2 ym=make_float2(d02.x+d13.y,d02.y-d13.x);
;   float2 yp=make_float2(d02.x-d13.y,d02.y+d13.x);
;   float2 y1, y3;
;   if (INV){ y1=yp; y3=ym; } else if (NOTW){ y1=ym; y3=yp; } else { y1=cmul(ym,w1); y2=cmul(y2,w2); y3=cmul(yp,w3); }
;   Z[i0]=y0; Z[i1]=y1; Z[i2]=y2; Z[i3]=y3;
; }
; template<bool INV, int LQ, bool BARRIER=true>
; HD void fft_pass(float2* Z, const float2* twA, const float2* twB, int tid){
;     ...
;   } else if (LQ==10){
;     _Pragma("unroll") for (int e=0;e<2;++e){ int j=tid+512*e; int k=j*tws;
;       float2 w1=cmul(twA[k>>6],twB[k&63]), w2=cmul(w1,w1), w3=cmul(w2,w1);
;       _Pragma("unroll") for (int ip=0;ip<4;++ip){ int base=ip*4096+j; bf4c<INV,false>(Z,base,base+q,base+2*q,base+3*q,w1,w2,w3); } }
;   } else {
;     int j=tid&(q-1); int base0=((tid>>LQ)<<(LQ+2))+j;
;     float2 w1=make_float2(1.f,0.f), w2=w1, w3=w1;
;     if (LQ>0){ int k=j*tws; w1=cmul(twA[k>>6],twB[k&63]); w2=cmul(w1,w1); w3=cmul(w2,w1); }
;     _Pragma("unroll") for (int i=0;i<8;++i){ int base=base0+i*2048; bf4c<INV,(LQ==0)>(Z,base,base+q,base+2*q,base+3*q,w1,w2,w3); }
;   }
;   if (BARRIER) __syncthreads(); else asm volatile("s_waitcnt lgkmcnt(0)" ::: "memory");
; }
; __device__ __forceinline__ void fft_fwd_head(float2* Z, const float2* twA, const float2* twB, int tid){
;   fft_pass<false,10>(Z,twA,twB,tid); fft_pass<false,8>(Z,twA,twB,tid); fft_pass<false,6,false>(Z,twA,twB,tid);
;   fft_pass<false,4,false>(Z,twA,twB,tid); fft_pass<false,2,false>(Z,twA,twB,tid);
; }
; __device__ __forceinline__ void fft_inv_tail(float2* Z, const float2* twA, const float2* twB, int tid){
;   fft_pass<true,2,false>(Z,twA,twB,tid); fft_pass<true,4,false>(Z,twA,twB,tid); fft_pass<true,6>(Z,twA,twB,tid);
;   fft_pass<true,8>(Z,twA,twB,tid); fft_pass<true,10>(Z,twA,twB,tid);
	v_pk_mul_f32 v[250:251], v[12:13], v[238:239] op_sel:[1,1] op_sel_hi:[0,1]
	v_pk_fma_f32 v[12:13], v[12:13], v[238:239], v[250:251] op_sel:[0,0,0] op_sel_hi:[1,0,1] neg_hi:[0,0,1]
	v_pk_mul_f32 v[250:251], v[10:11], v[236:237] op_sel:[1,1] op_sel_hi:[0,1]
	v_pk_fma_f32 v[10:11], v[10:11], v[236:237], v[250:251] op_sel:[0,0,0] op_sel_hi:[1,0,1] neg_hi:[0,0,1]
	v_pk_mul_f32 v[250:251], v[14:15], v[240:241] op_sel:[1,1] op_sel_hi:[0,1]
	v_pk_fma_f32 v[14:15], v[14:15], v[240:241], v[250:251] op_sel:[0,0,0] op_sel_hi:[1,0,1] neg_hi:[0,0,1]
	v_pk_add_f32 v[242:243], v[8:9], v[12:13]
	v_pk_add_f32 v[244:245], v[8:9], v[12:13] neg_lo:[0,1] neg_hi:[0,1]
	v_pk_add_f32 v[246:247], v[10:11], v[14:15]
	v_pk_add_f32 v[248:249], v[10:11], v[14:15] neg_lo:[0,1] neg_hi:[0,1]
	v_pk_add_f32 v[8:9], v[242:243], v[246:247]
	v_pk_add_f32 v[10:11], v[244:245], v[248:249] op_sel:[0,1] op_sel_hi:[1,0] neg_lo:[0,1]
	v_pk_add_f32 v[12:13], v[242:243], v[246:247] neg_lo:[0,1] neg_hi:[0,1]
	v_pk_add_f32 v[14:15], v[244:245], v[248:249] op_sel:[0,1] op_sel_hi:[1,0] neg_hi:[0,1]
	s_waitcnt lgkmcnt(4)
	v_pk_mul_f32 v[250:251], v[20:21], v[238:239] op_sel:[1,1] op_sel_hi:[0,1]
	v_pk_fma_f32 v[20:21], v[20:21], v[238:239], v[250:251] op_sel:[0,0,0] op_sel_hi:[1,0,1] neg_hi:[0,0,1]
	v_pk_mul_f32 v[250:251], v[18:19], v[236:237] op_sel:[1,1] op_sel_hi:[0,1]
	v_pk_fma_f32 v[18:19], v[18:19], v[236:237], v[250:251] op_sel:[0,0,0] op_sel_hi:[1,0,1] neg_hi:[0,0,1]
	v_pk_mul_f32 v[250:251], v[22:23], v[240:241] op_sel:[1,1] op_sel_hi:[0,1]
	v_pk_fma_f32 v[22:23], v[22:23], v[240:241], v[250:251] op_sel:[0,0,0] op_sel_hi:[1,0,1] neg_hi:[0,0,1]
	v_pk_add_f32 v[242:243], v[16:17], v[20:21]
	v_pk_add_f32 v[244:245], v[16:17], v[20:21] neg_lo:[0,1] neg_hi:[0,1]
	v_pk_add_f32 v[246:247], v[18:19], v[22:23]
	v_pk_add_f32 v[248:249], v[18:19], v[22:23] neg_lo:[0,1] neg_hi:[0,1]
	v_pk_add_f32 v[16:17], v[242:243], v[246:247]
	v_pk_add_f32 v[18:19], v[244:245], v[248:249] op_sel:[0,1] op_sel_hi:[1,0] neg_lo:[0,1]
	v_pk_add_f32 v[20:21], v[242:243], v[246:247] neg_lo:[0,1] neg_hi:[0,1]
	v_pk_add_f32 v[22:23], v[244:245], v[248:249] op_sel:[0,1] op_sel_hi:[1,0] neg_hi:[0,1]
	s_waitcnt lgkmcnt(0)
	v_pk_mul_f32 v[250:251], v[28:29], v[238:239] op_sel:[1,1] op_sel_hi:[0,1]
	v_pk_fma_f32 v[28:29], v[28:29], v[238:239], v[250:251] op_sel:[0,0,0] op_sel_hi:[1,0,1] neg_hi:[0,0,1]
	v_pk_mul_f32 v[250:251], v[26:27], v[236:237] op_sel:[1,1] op_sel_hi:[0,1]
	v_pk_fma_f32 v[26:27], v[26:27], v[236:237], v[250:251] op_sel:[0,0,0] op_sel_hi:[1,0,1] neg_hi:[0,0,1]
	v_pk_mul_f32 v[250:251], v[30:31], v[240:241] op_sel:[1,1] op_sel_hi:[0,1]
	v_pk_fma_f32 v[30:31], v[30:31], v[240:241], v[250:251] op_sel:[0,0,0] op_sel_hi:[1,0,1] neg_hi:[0,0,1]
	v_pk_add_f32 v[242:243], v[24:25], v[28:29]
	v_pk_add_f32 v[244:245], v[24:25], v[28:29] neg_lo:[0,1] neg_hi:[0,1]
	v_pk_add_f32 v[246:247], v[26:27], v[30:31]
	v_pk_add_f32 v[248:249], v[26:27], v[30:31] neg_lo:[0,1] neg_hi:[0,1]
	v_pk_add_f32 v[24:25], v[242:243], v[246:247]
	v_pk_add_f32 v[26:27], v[244:245], v[248:249] op_sel:[0,1] op_sel_hi:[1,0] neg_lo:[0,1]
	v_pk_add_f32 v[28:29], v[242:243], v[246:247] neg_lo:[0,1] neg_hi:[0,1]
	v_pk_add_f32 v[30:31], v[244:245], v[248:249] op_sel:[0,1] op_sel_hi:[1,0] neg_hi:[0,1]
	v_pk_mul_f32 v[250:251], v[16:17], v[82:83] op_sel:[1,1] op_sel_hi:[0,1]
	v_pk_fma_f32 v[16:17], v[16:17], v[82:83], v[250:251] op_sel:[0,0,0] op_sel_hi:[1,0,1] neg_hi:[0,0,1]
	v_pk_mul_f32 v[250:251], v[8:9], v[80:81] op_sel:[1,1] op_sel_hi:[0,1]
	v_pk_fma_f32 v[8:9], v[8:9], v[80:81], v[250:251] op_sel:[0,0,0] op_sel_hi:[1,0,1] neg_hi:[0,0,1]
	v_pk_mul_f32 v[250:251], v[24:25], v[84:85] op_sel:[1,1] op_sel_hi:[0,1]
	v_pk_fma_f32 v[24:25], v[24:25], v[84:85], v[250:251] op_sel:[0,0,0] op_sel_hi:[1,0,1] neg_hi:[0,0,1]
	v_pk_add_f32 v[242:243], v[0:1], v[16:17]
	v_pk_add_f32 v[244:245], v[0:1], v[16:17] neg_lo:[0,1] neg_hi:[0,1]
	v_pk_add_f32 v[246:247], v[8:9], v[24:25]
	v_pk_add_f32 v[248:249], v[8:9], v[24:25] neg_lo:[0,1] neg_hi:[0,1]
	v_pk_add_f32 v[0:1], v[242:243], v[246:247]
	ds_write_b64 v227, v[0:1] offset:0
	v_pk_add_f32 v[8:9], v[244:245], v[248:249] op_sel:[0,1] op_sel_hi:[1,0] neg_lo:[0,1]
	ds_write_b64 v227, v[8:9] offset:8192
	v_pk_add_f32 v[16:17], v[242:243], v[246:247] neg_lo:[0,1] neg_hi:[0,1]
	ds_write_b64 v227, v[16:17] offset:16384
	v_pk_add_f32 v[24:25], v[244:245], v[248:249] op_sel:[0,1] op_sel_hi:[1,0] neg_hi:[0,1]
	ds_write_b64 v227, v[24:25] offset:24576
	v_pk_mul_f32 v[250:251], v[18:19], v[224:225] op_sel:[1,1] op_sel_hi:[1,0] neg_lo:[0,0] neg_hi:[0,0]
	v_pk_fma_f32 v[18:19], v[18:19], v[224:225], v[250:251] op_sel:[0,0,0] op_sel_hi:[0,1,1] neg_lo:[0,0,1] neg_hi:[0,0,0]
	v_pk_mul_f32 v[250:251], v[18:19], v[82:83] op_sel:[1,1] op_sel_hi:[0,1]
	v_pk_fma_f32 v[18:19], v[18:19], v[82:83], v[250:251] op_sel:[0,0,0] op_sel_hi:[1,0,1] neg_hi:[0,0,1]
	v_pk_mul_f32 v[250:251], v[10:11], v[222:223] op_sel:[1,1] op_sel_hi:[1,0] neg_lo:[0,0] neg_hi:[0,0]
	v_pk_fma_f32 v[10:11], v[10:11], v[222:223], v[250:251] op_sel:[0,0,0] op_sel_hi:[0,1,1] neg_lo:[0,0,1] neg_hi:[0,0,0]
	v_pk_mul_f32 v[250:251], v[10:11], v[80:81] op_sel:[1,1] op_sel_hi:[0,1]
	v_pk_fma_f32 v[10:11], v[10:11], v[80:81], v[250:251] op_sel:[0,0,0] op_sel_hi:[1,0,1] neg_hi:[0,0,1]
	v_pk_mul_f32 v[250:251], v[26:27], v[222:223] op_sel:[1,0] op_sel_hi:[1,1] neg_lo:[0,0] neg_hi:[0,0]
	v_pk_fma_f32 v[26:27], v[26:27], v[222:223], v[250:251] op_sel:[0,1,0] op_sel_hi:[0,0,1] neg_lo:[0,0,1] neg_hi:[0,0,0]
	v_pk_mul_f32 v[250:251], v[26:27], v[84:85] op_sel:[1,1] op_sel_hi:[0,1]
	v_pk_fma_f32 v[26:27], v[26:27], v[84:85], v[250:251] op_sel:[0,0,0] op_sel_hi:[1,0,1] neg_hi:[0,0,1]
; HD float2 cmul(float2 a, float2 b){ return make_float2(a.x*b.x - a.y*b.y, a.x*b.y + a.y*b.x); }
; template<bool INV, bool NOTW>
; HD void bf4c(float2* Z, int i0, int i1, int i2, int i3, float2 w1, float2 w2, float2 w3){
;   float2 a0=Z[i0], a1=Z[i1], a2=Z[i2], a3=Z[i3];
;   if (INV && !NOTW){ a1=cmulc(a1,w1); a2=cmulc(a2,w2); a3=cmulc(a3,w3); }
;   float2 s02=make_float2(a0.x+a2.x,a0.y+a2.y), d02=make_float2(a0.x-a2.x,a0.y-a2.y);
;   float2 s13=make_float2(a1.x+a3.x,a1.y+a3.y), d13=make_float2(a1.x-a3.x,a1.y-a3.y);
;   float2 y0=make_float2(s02.x+s13.x,s02.y+s13.y), y2=make_float2(s02.x-s13.x,s02.y-s13.y);
;   float2 ym=make_float2(d02.x+d13.y,d02.y-d13.x);
;   float2 yp=make_float2(d02.x-d13.y,d02.y+d13.x);
;   float2 y1, y3;
;   if (INV){ y1=yp; y3=ym; } else if (NOTW){ y1=ym; y3=yp; } else { y1=cmul(ym,w1); y2=cmul(y2,w2); y3=cmul(yp,w3); }
;   Z[i0]=y0; Z[i1]=y1; Z[i2]=y2; Z[i3]=y3;
; }
; template<bool INV, int LQ, bool BARRIER=true>
; HD void fft_pass(float2* Z, const float2* twA, const float2* twB, int tid){
;     ...
;   } else if (LQ==10){
;     _Pragma("unroll") for (int e=0;e<2;++e){ int j=tid+512*e; int k=j*tws;
;       float2 w1=cmul(twA[k>>6],twB[k&63]), w2=cmul(w1,w1), w3=cmul(w2,w1);
;       _Pragma("unroll") for (int ip=0;ip<4;++ip){ int base=ip*4096+j; bf4c<INV,false>(Z,base,base+q,base+2*q,base+3*q,w1,w2,w3); } }
;   } else {
;     int j=tid&(q-1); int base0=((tid>>LQ)<<(LQ+2))+j;
;     float2 w1=make_float2(1.f,0.f), w2=w1, w3=w1;
;     if (LQ>0){ int k=j*tws; w1=cmul(twA[k>>6],twB[k&63]); w2=cmul(w1,w1); w3=cmul(w2,w1); }
;     _Pragma("unroll") for (int i=0;i<8;++i){ int base=base0+i*2048; bf4c<INV,(LQ==0)>(Z,base,base+q,base+2*q,base+3*q,w1,w2,w3); }
;   }
;   if (BARRIER) __syncthreads(); else asm volatile("s_waitcnt lgkmcnt(0)" ::: "memory");
; }
; __device__ __forceinline__ void fft_fwd_head(float2* Z, const float2* twA, const float2* twB, int tid){
;   fft_pass<false,10>(Z,twA,twB,tid); fft_pass<false,8>(Z,twA,twB,tid); fft_pass<false,6,false>(Z,twA,twB,tid);
;   fft_pass<false,4,false>(Z,twA,twB,tid); fft_pass<false,2,false>(Z,twA,twB,tid);
; }
; __device__ __forceinline__ void fft_inv_tail(float2* Z, const float2* twA, const float2* twB, int tid){
;   fft_pass<true,2,false>(Z,twA,twB,tid); fft_pass<true,4,false>(Z,twA,twB,tid); fft_pass<true,6>(Z,twA,twB,tid);
;   fft_pass<true,8>(Z,twA,twB,tid); fft_pass<true,10>(Z,twA,twB,tid);
	v_pk_add_f32 v[242:243], v[2:3], v[18:19]
	v_pk_add_f32 v[244:245], v[2:3], v[18:19] neg_lo:[0,1] neg_hi:[0,1]
	v_pk_add_f32 v[246:247], v[10:11], v[26:27]
	v_pk_add_f32 v[248:249], v[10:11], v[26:27] neg_lo:[0,1] neg_hi:[0,1]
	v_pk_add_f32 v[2:3], v[242:243], v[246:247]
	ds_write_b64 v227, v[2:3] offset:2048
	v_pk_add_f32 v[10:11], v[244:245], v[248:249] op_sel:[0,1] op_sel_hi:[1,0] neg_lo:[0,1]
	ds_write_b64 v227, v[10:11] offset:10240
	v_pk_add_f32 v[18:19], v[242:243], v[246:247] neg_lo:[0,1] neg_hi:[0,1]
	ds_write_b64 v227, v[18:19] offset:18432
	v_pk_add_f32 v[26:27], v[244:245], v[248:249] op_sel:[0,1] op_sel_hi:[1,0] neg_hi:[0,1]
	ds_write_b64 v227, v[26:27] offset:26624
	v_pk_add_f32 v[20:21], v[20:21], 0 op_sel:[1,0] op_sel_hi:[0,0] neg_lo:[1,0]
	v_pk_mul_f32 v[250:251], v[20:21], v[82:83] op_sel:[1,1] op_sel_hi:[0,1]
	v_pk_fma_f32 v[20:21], v[20:21], v[82:83], v[250:251] op_sel:[0,0,0] op_sel_hi:[1,0,1] neg_hi:[0,0,1]
	v_pk_mul_f32 v[250:251], v[12:13], v[224:225] op_sel:[1,1] op_sel_hi:[1,0] neg_lo:[0,0] neg_hi:[0,0]
	v_pk_fma_f32 v[12:13], v[12:13], v[224:225], v[250:251] op_sel:[0,0,0] op_sel_hi:[0,1,1] neg_lo:[0,0,1] neg_hi:[0,0,0]
	v_pk_mul_f32 v[250:251], v[12:13], v[80:81] op_sel:[1,1] op_sel_hi:[0,1]
	v_pk_fma_f32 v[12:13], v[12:13], v[80:81], v[250:251] op_sel:[0,0,0] op_sel_hi:[1,0,1] neg_hi:[0,0,1]
	v_pk_mul_f32 v[250:251], v[28:29], v[224:225] op_sel:[1,1] op_sel_hi:[1,0] neg_lo:[0,0] neg_hi:[0,1]
	v_pk_fma_f32 v[28:29], v[28:29], v[224:225], v[250:251] op_sel:[0,0,0] op_sel_hi:[0,1,1] neg_lo:[0,1,1] neg_hi:[0,0,0]
	v_pk_mul_f32 v[250:251], v[28:29], v[84:85] op_sel:[1,1] op_sel_hi:[0,1]
	v_pk_fma_f32 v[28:29], v[28:29], v[84:85], v[250:251] op_sel:[0,0,0] op_sel_hi:[1,0,1] neg_hi:[0,0,1]
	v_pk_add_f32 v[242:243], v[4:5], v[20:21]
	v_pk_add_f32 v[244:245], v[4:5], v[20:21] neg_lo:[0,1] neg_hi:[0,1]
	v_pk_add_f32 v[246:247], v[12:13], v[28:29]
	v_pk_add_f32 v[248:249], v[12:13], v[28:29] neg_lo:[0,1] neg_hi:[0,1]
	v_pk_add_f32 v[4:5], v[242:243], v[246:247]
	ds_write_b64 v227, v[4:5] offset:4096
	v_pk_add_f32 v[12:13], v[244:245], v[248:249] op_sel:[0,1] op_sel_hi:[1,0] neg_lo:[0,1]
	ds_write_b64 v227, v[12:13] offset:12288
	v_pk_add_f32 v[20:21], v[242:243], v[246:247] neg_lo:[0,1] neg_hi:[0,1]
	ds_write_b64 v227, v[20:21] offset:20480
	v_pk_add_f32 v[28:29], v[244:245], v[248:249] op_sel:[0,1] op_sel_hi:[1,0] neg_hi:[0,1]
	ds_write_b64 v227, v[28:29] offset:28672
	v_pk_mul_f32 v[250:251], v[22:23], v[224:225] op_sel:[1,1] op_sel_hi:[1,0] neg_lo:[0,0] neg_hi:[0,1]
	v_pk_fma_f32 v[22:23], v[22:23], v[224:225], v[250:251] op_sel:[0,0,0] op_sel_hi:[0,1,1] neg_lo:[0,1,1] neg_hi:[0,0,0]
	v_pk_mul_f32 v[250:251], v[22:23], v[82:83] op_sel:[1,1] op_sel_hi:[0,1]
	v_pk_fma_f32 v[22:23], v[22:23], v[82:83], v[250:251] op_sel:[0,0,0] op_sel_hi:[1,0,1] neg_hi:[0,0,1]
	v_pk_mul_f32 v[250:251], v[14:15], v[222:223] op_sel:[1,0] op_sel_hi:[1,1] neg_lo:[0,0] neg_hi:[0,0]
	v_pk_fma_f32 v[14:15], v[14:15], v[222:223], v[250:251] op_sel:[0,1,0] op_sel_hi:[0,0,1] neg_lo:[0,0,1] neg_hi:[0,0,0]
	v_pk_mul_f32 v[250:251], v[14:15], v[80:81] op_sel:[1,1] op_sel_hi:[0,1]
	v_pk_fma_f32 v[14:15], v[14:15], v[80:81], v[250:251] op_sel:[0,0,0] op_sel_hi:[1,0,1] neg_hi:[0,0,1]
	v_pk_mul_f32 v[250:251], v[30:31], v[222:223] op_sel:[1,1] op_sel_hi:[1,0] neg_lo:[0,1] neg_hi:[0,1]
	v_pk_fma_f32 v[30:31], v[30:31], v[222:223], v[250:251] op_sel:[0,0,0] op_sel_hi:[0,1,1] neg_lo:[0,1,1] neg_hi:[0,1,0]
	v_pk_mul_f32 v[250:251], v[30:31], v[84:85] op_sel:[1,1] op_sel_hi:[0,1]
	v_pk_fma_f32 v[30:31], v[30:31], v[84:85], v[250:251] op_sel:[0,0,0] op_sel_hi:[1,0,1] neg_hi:[0,0,1]
	v_pk_add_f32 v[242:243], v[6:7], v[22:23]
	v_pk_add_f32 v[244:245], v[6:7], v[22:23] neg_lo:[0,1] neg_hi:[0,1]
	v_pk_add_f32 v[246:247], v[14:15], v[30:31]
	v_pk_add_f32 v[248:249], v[14:15], v[30:31] neg_lo:[0,1] neg_hi:[0,1]
	v_pk_add_f32 v[6:7], v[242:243], v[246:247]
	ds_write_b64 v227, v[6:7] offset:6144
	v_pk_add_f32 v[14:15], v[244:245], v[248:249] op_sel:[0,1] op_sel_hi:[1,0] neg_lo:[0,1]
	ds_write_b64 v227, v[14:15] offset:14336
	v_pk_add_f32 v[22:23], v[242:243], v[246:247] neg_lo:[0,1] neg_hi:[0,1]
	ds_write_b64 v227, v[22:23] offset:22528
	v_pk_add_f32 v[30:31], v[244:245], v[248:249] op_sel:[0,1] op_sel_hi:[1,0] neg_hi:[0,1]
	ds_write_b64 v227, v[30:31] offset:30720
	s_waitcnt lgkmcnt(0)
	s_barrier
	s_mov_b64 s[12:13], -1
	s_and_b64 vcc, exec, s[50:51]
	s_cbranch_vccz .LBB0_1340
; __device__ __forceinline__ float bf2f(u16 h){ return __uint_as_float(((unsigned)h)<<16); }
; __device__ __forceinline__ float hconv3(const u16* __restrict__ row, int t, float w0, float w1, float w2, float bias){
;   float m = bf2f(row[t]);
;   int mi=__float_as_int(m);
;   float l=__int_as_float(__builtin_amdgcn_update_dpp(0, mi, 0x138, 0xf, 0xf, false));
;   float r=__int_as_float(__builtin_amdgcn_update_dpp(0, mi, 0x130, 0xf, 0xf, false));
;   return w0*l+w1*m+w2*r+bias;
; }
; __device__ __forceinline__ void phase_hyena(KP kp_, int hf){ asm volatile("" : "+s"(kp_)); const Params p=load_params(kp_);
;     ...
;           _Pragma("unroll 4") for (int i=0;i<8;++i){ int tb=tq+512*i; float2 xr[2]; inv12_half(Z,twA,twB,tb,xr[0],xr[1]);
;             _Pragma("unroll") for (int hh=0;hh<2;++hh){ int t=tb+hh*4096;
;               float x0=hconv3(r2,t,wb0,wb1,wb2,bb_), x1=hconv3(r2+8192,t,wb0,wb1,wb2,bb_);
;               float2 y=xr[hh]; y.x*=(1.f/16384.f); y.y*=(1.f/16384.f); float2 z1=Zs[t];
;               float o0=x0*(y.x+z1.x*bias1)*bf2f(rz[t]); float o1=x1*(y.y+z1.y*bias1)*bf2f(rz[8192+t]);
;               ybT[(size_t)c*16384+t]=f2bf(o0); ybT[(size_t)c*16384+8192+t]=f2bf(o1); } }
	v_lshlrev_b32_e32 v0, 1, v86
	v_add_u32_e32 v1, 0x1000, v0
	v_add_u32_e32 v2, 0x2000, v0
	v_add_u32_e32 v4, 0x3000, v0
	v_lshlrev_b32_e32 v5, 3, v86
	v_mov_b32_e32 v8, v5
	v_add_u32_e32 v9, 0x10000, v5
	v_lshrrev_b32_e32 v7, 6, v86
	v_lshl_add_u32 v7, v7, 3, s88
	v_and_b32_e32 v108, 63, v86
	v_lshl_add_u32 v108, v108, 3, s91
	ds_read_b64 v[10:11], v108
	s_add_u32 s12, s72, 0x4000
	s_addc_u32 s13, s73, 0
	s_add_u32 s50, s80, 0x8000
	s_addc_u32 s51, s81, 0
	v_mov_b32_e32 v107, 0
	v_mov_b32_e32 v160, 0x38800000
	v_mov_b32_e32 v161, 0x38800000
	v_mov_b32_e32 v106, v0
	v_lshl_add_u64 v[110:111], v[54:55], 0, v[106:107]
	v_lshl_add_u64 v[118:119], v[56:57], 0, v[106:107]
	v_mov_b32_e32 v106, v1
	v_lshl_add_u64 v[112:113], v[54:55], 0, v[106:107]
	v_lshl_add_u64 v[120:121], v[56:57], 0, v[106:107]
	v_mov_b32_e32 v106, v2
	v_lshl_add_u64 v[114:115], v[54:55], 0, v[106:107]
	v_lshl_add_u64 v[122:123], v[56:57], 0, v[106:107]
	v_mov_b32_e32 v106, v4
	v_lshl_add_u64 v[116:117], v[54:55], 0, v[106:107]
	v_lshl_add_u64 v[124:125], v[56:57], 0, v[106:107]
	global_load_ushort v228, v0, s[96:97] offset:0
	global_load_ushort v230, v0, s[74:75] offset:0
	global_load_ushort v232, v0, s[72:73] offset:0
	global_load_ushort v234, v0, s[12:13] offset:0
	global_load_ushort v229, v2, s[96:97] offset:0
	global_load_ushort v231, v2, s[74:75] offset:0
	global_load_ushort v233, v2, s[72:73] offset:0
	global_load_ushort v235, v2, s[12:13] offset:0
	v_mov_b32_e32 v6, v5
	global_load_dwordx2 v[236:237], v6, s[80:81] sc1
	global_load_dwordx2 v[238:239], v6, s[50:51] sc1
	ds_read_b64 v[12:13], v7 offset:0
	ds_read_b64 v[14:15], v8 offset:0
	ds_read_b64 v[16:17], v8 offset:32768
	ds_read_b64 v[18:19], v9 offset:0
	ds_read_b64 v[20:21], v9 offset:32768
	global_load_ushort v240, v0, s[96:97] offset:1024
	global_load_ushort v242, v0, s[74:75] offset:1024
	global_load_ushort v244, v0, s[72:73] offset:1024
	global_load_ushort v246, v0, s[12:13] offset:1024
	global_load_ushort v241, v2, s[96:97] offset:1024
	global_load_ushort v243, v2, s[74:75] offset:1024
	global_load_ushort v245, v2, s[72:73] offset:1024
	global_load_ushort v247, v2, s[12:13] offset:1024
	v_add_u32_e32 v6, 0x1000, v5
	global_load_dwordx2 v[248:249], v6, s[80:81] sc1
	global_load_dwordx2 v[250:251], v6, s[50:51] sc1
	ds_read_b64 v[58:59], v7 offset:64
	ds_read_b64 v[60:61], v8 offset:4096
	ds_read_b64 v[62:63], v8 offset:36864
	ds_read_b64 v[64:65], v9 offset:4096
	ds_read_b64 v[66:67], v9 offset:36864
	s_waitcnt lgkmcnt(5)
	v_pk_mul_f32 v[222:223], v[12:13], v[10:11] op_sel:[1,1] op_sel_hi:[1,0]
	v_pk_fma_f32 v[22:23], v[12:13], v[10:11], v[222:223] op_sel:[0,0,0] op_sel_hi:[0,1,1] neg_lo:[0,0,1]
	v_pk_mul_f32 v[222:223], v[22:23], v[22:23] op_sel:[1,1] op_sel_hi:[1,0]
	v_pk_fma_f32 v[24:25], v[22:23], v[22:23], v[222:223] op_sel:[0,0,0] op_sel_hi:[0,1,1] neg_lo:[0,0,1]
	v_pk_mul_f32 v[222:223], v[24:25], v[22:23] op_sel:[1,1] op_sel_hi:[1,0]
	v_pk_fma_f32 v[26:27], v[24:25], v[22:23], v[222:223] op_sel:[0,0,0] op_sel_hi:[0,1,1] neg_lo:[0,0,1]
	v_pk_mul_f32 v[222:223], v[16:17], v[22:23] op_sel:[1,1] op_sel_hi:[0,1]
	v_pk_fma_f32 v[28:29], v[16:17], v[22:23], v[222:223] op_sel:[0,0,0] op_sel_hi:[1,0,1] neg_hi:[0,0,1]
	v_pk_mul_f32 v[222:223], v[18:19], v[24:25] op_sel:[1,1] op_sel_hi:[0,1]
	v_pk_fma_f32 v[30:31], v[18:19], v[24:25], v[222:223] op_sel:[0,0,0] op_sel_hi:[1,0,1] neg_hi:[0,0,1]
	v_pk_mul_f32 v[222:223], v[20:21], v[26:27] op_sel:[1,1] op_sel_hi:[0,1]
	v_pk_fma_f32 v[68:69], v[20:21], v[26:27], v[222:223] op_sel:[0,0,0] op_sel_hi:[1,0,1] neg_hi:[0,0,1]
	v_pk_add_f32 v[70:71], v[14:15], v[30:31]
	v_pk_add_f32 v[72:73], v[14:15], v[30:31] neg_lo:[0,1] neg_hi:[0,1]
	v_pk_add_f32 v[74:75], v[28:29], v[68:69]
	v_pk_add_f32 v[80:81], v[28:29], v[68:69] neg_lo:[0,1] neg_hi:[0,1]
	v_pk_add_f32 v[82:83], v[70:71], v[74:75]
	v_pk_add_f32 v[84:85], v[72:73], v[80:81] op_sel:[0,1] op_sel_hi:[1,0] neg_lo:[0,1]
	s_waitcnt vmcnt(10)
	v_lshlrev_b32_e32 v224, 16, v228
	v_lshlrev_b32_e32 v225, 16, v230
	v_pk_mul_f32 v[226:227], v[224:225], v[88:89] op_sel_hi:[1,0]
	v_fmac_f32_dpp v226, v224, v87 wave_shr:1 row_mask:0xf bank_mask:0xf
	v_fmac_f32_dpp v227, v225, v87 wave_shr:1 row_mask:0xf bank_mask:0xf
	v_fmac_f32_dpp v226, v224, v89 wave_shl:1 row_mask:0xf bank_mask:0xf
	v_fmac_f32_dpp v227, v225, v89 wave_shl:1 row_mask:0xf bank_mask:0xf
	v_pk_add_f32 v[150:151], v[226:227], v[90:91] op_sel_hi:[1,0]
	v_lshlrev_b32_e32 v224, 16, v229
	v_lshlrev_b32_e32 v225, 16, v231
	v_pk_mul_f32 v[226:227], v[224:225], v[88:89] op_sel_hi:[1,0]
	v_fmac_f32_dpp v226, v224, v87 wave_shr:1 row_mask:0xf bank_mask:0xf
	v_fmac_f32_dpp v227, v225, v87 wave_shr:1 row_mask:0xf bank_mask:0xf
	v_fmac_f32_dpp v226, v224, v89 wave_shl:1 row_mask:0xf bank_mask:0xf
	v_fmac_f32_dpp v227, v225, v89 wave_shl:1 row_mask:0xf bank_mask:0xf
	v_pk_add_f32 v[152:153], v[226:227], v[90:91] op_sel_hi:[1,0]
	v_pk_mul_f32 v[158:159], v[236:237], v[90:91] op_sel:[0,1] op_sel_hi:[1,1]
	v_pk_fma_f32 v[158:159], v[82:83], v[160:161], v[158:159]
	v_pk_mul_f32 v[158:159], v[150:151], v[158:159]
	v_lshlrev_b32_e32 v156, 16, v232
	v_lshlrev_b32_e32 v157, 16, v234
	v_pk_mul_f32 v[158:159], v[158:159], v[156:157]
	v_cvt_pk_bf16_f32 v224, v158, v159
	global_store_short v[110:111], v224, off offset:0
	global_store_short_d16_hi v[118:119], v224, off offset:0
	v_pk_mul_f32 v[158:159], v[238:239], v[90:91] op_sel:[0,1] op_sel_hi:[1,1]
	v_pk_fma_f32 v[158:159], v[84:85], v[160:161], v[158:159]
	v_pk_mul_f32 v[158:159], v[152:153], v[158:159]
	v_lshlrev_b32_e32 v156, 16, v233
	v_lshlrev_b32_e32 v157, 16, v235
	v_pk_mul_f32 v[158:159], v[158:159], v[156:157]
	v_cvt_pk_bf16_f32 v224, v158, v159
	global_store_short v[114:115], v224, off offset:0
	global_store_short_d16_hi v[122:123], v224, off offset:0
	global_load_ushort v228, v0, s[96:97] offset:2048
	global_load_ushort v230, v0, s[74:75] offset:2048
	global_load_ushort v232, v0, s[72:73] offset:2048
	global_load_ushort v234, v0, s[12:13] offset:2048
	global_load_ushort v229, v2, s[96:97] offset:2048
	global_load_ushort v231, v2, s[74:75] offset:2048
	global_load_ushort v233, v2, s[72:73] offset:2048
	global_load_ushort v235, v2, s[12:13] offset:2048
	v_add_u32_e32 v6, 0x2000, v5
	global_load_dwordx2 v[236:237], v6, s[80:81] sc1
	global_load_dwordx2 v[238:239], v6, s[50:51] sc1
	ds_read_b64 v[12:13], v7 offset:128
	ds_read_b64 v[14:15], v8 offset:8192
	ds_read_b64 v[16:17], v8 offset:40960
	ds_read_b64 v[18:19], v9 offset:8192
	ds_read_b64 v[20:21], v9 offset:40960
	s_waitcnt lgkmcnt(5)
; __device__ __forceinline__ float bf2f(u16 h){ return __uint_as_float(((unsigned)h)<<16); }
; __device__ __forceinline__ float hconv3(const u16* __restrict__ row, int t, float w0, float w1, float w2, float bias){
;   float m = bf2f(row[t]);
;   int mi=__float_as_int(m);
;   float l=__int_as_float(__builtin_amdgcn_update_dpp(0, mi, 0x138, 0xf, 0xf, false));
;   float r=__int_as_float(__builtin_amdgcn_update_dpp(0, mi, 0x130, 0xf, 0xf, false));
;   return w0*l+w1*m+w2*r+bias;
; }
; __device__ __forceinline__ void phase_hyena(KP kp_, int hf){ asm volatile("" : "+s"(kp_)); const Params p=load_params(kp_);
;     ...
;           _Pragma("unroll 4") for (int i=0;i<8;++i){ int tb=tq+512*i; float2 xr[2]; inv12_half(Z,twA,twB,tb,xr[0],xr[1]);
;             _Pragma("unroll") for (int hh=0;hh<2;++hh){ int t=tb+hh*4096;
;               float x0=hconv3(r2,t,wb0,wb1,wb2,bb_), x1=hconv3(r2+8192,t,wb0,wb1,wb2,bb_);
;               float2 y=xr[hh]; y.x*=(1.f/16384.f); y.y*=(1.f/16384.f); float2 z1=Zs[t];
;               float o0=x0*(y.x+z1.x*bias1)*bf2f(rz[t]); float o1=x1*(y.y+z1.y*bias1)*bf2f(rz[8192+t]);
;               ybT[(size_t)c*16384+t]=f2bf(o0); ybT[(size_t)c*16384+8192+t]=f2bf(o1); } }
	v_pk_mul_f32 v[222:223], v[58:59], v[10:11] op_sel:[1,1] op_sel_hi:[1,0]
	v_pk_fma_f32 v[22:23], v[58:59], v[10:11], v[222:223] op_sel:[0,0,0] op_sel_hi:[0,1,1] neg_lo:[0,0,1]
	v_pk_mul_f32 v[222:223], v[22:23], v[22:23] op_sel:[1,1] op_sel_hi:[1,0]
	v_pk_fma_f32 v[24:25], v[22:23], v[22:23], v[222:223] op_sel:[0,0,0] op_sel_hi:[0,1,1] neg_lo:[0,0,1]
	v_pk_mul_f32 v[222:223], v[24:25], v[22:23] op_sel:[1,1] op_sel_hi:[1,0]
	v_pk_fma_f32 v[26:27], v[24:25], v[22:23], v[222:223] op_sel:[0,0,0] op_sel_hi:[0,1,1] neg_lo:[0,0,1]
	v_pk_mul_f32 v[222:223], v[62:63], v[22:23] op_sel:[1,1] op_sel_hi:[0,1]
	v_pk_fma_f32 v[28:29], v[62:63], v[22:23], v[222:223] op_sel:[0,0,0] op_sel_hi:[1,0,1] neg_hi:[0,0,1]
	v_pk_mul_f32 v[222:223], v[64:65], v[24:25] op_sel:[1,1] op_sel_hi:[0,1]
	v_pk_fma_f32 v[30:31], v[64:65], v[24:25], v[222:223] op_sel:[0,0,0] op_sel_hi:[1,0,1] neg_hi:[0,0,1]
	v_pk_mul_f32 v[222:223], v[66:67], v[26:27] op_sel:[1,1] op_sel_hi:[0,1]
	v_pk_fma_f32 v[68:69], v[66:67], v[26:27], v[222:223] op_sel:[0,0,0] op_sel_hi:[1,0,1] neg_hi:[0,0,1]
	v_pk_add_f32 v[70:71], v[60:61], v[30:31]
	v_pk_add_f32 v[72:73], v[60:61], v[30:31] neg_lo:[0,1] neg_hi:[0,1]
	v_pk_add_f32 v[74:75], v[28:29], v[68:69]
	v_pk_add_f32 v[80:81], v[28:29], v[68:69] neg_lo:[0,1] neg_hi:[0,1]
	v_pk_add_f32 v[82:83], v[70:71], v[74:75]
	v_pk_add_f32 v[84:85], v[72:73], v[80:81] op_sel:[0,1] op_sel_hi:[1,0] neg_lo:[0,1]
	s_waitcnt vmcnt(14)
	v_lshlrev_b32_e32 v224, 16, v240
	v_lshlrev_b32_e32 v225, 16, v242
	v_pk_mul_f32 v[226:227], v[224:225], v[88:89] op_sel_hi:[1,0]
	v_fmac_f32_dpp v226, v224, v87 wave_shr:1 row_mask:0xf bank_mask:0xf
	v_fmac_f32_dpp v227, v225, v87 wave_shr:1 row_mask:0xf bank_mask:0xf
	v_fmac_f32_dpp v226, v224, v89 wave_shl:1 row_mask:0xf bank_mask:0xf
	v_fmac_f32_dpp v227, v225, v89 wave_shl:1 row_mask:0xf bank_mask:0xf
	v_pk_add_f32 v[150:151], v[226:227], v[90:91] op_sel_hi:[1,0]
	v_lshlrev_b32_e32 v224, 16, v241
	v_lshlrev_b32_e32 v225, 16, v243
	v_pk_mul_f32 v[226:227], v[224:225], v[88:89] op_sel_hi:[1,0]
	v_fmac_f32_dpp v226, v224, v87 wave_shr:1 row_mask:0xf bank_mask:0xf
	v_fmac_f32_dpp v227, v225, v87 wave_shr:1 row_mask:0xf bank_mask:0xf
	v_fmac_f32_dpp v226, v224, v89 wave_shl:1 row_mask:0xf bank_mask:0xf
	v_fmac_f32_dpp v227, v225, v89 wave_shl:1 row_mask:0xf bank_mask:0xf
	v_pk_add_f32 v[152:153], v[226:227], v[90:91] op_sel_hi:[1,0]
	v_pk_mul_f32 v[158:159], v[248:249], v[90:91] op_sel:[0,1] op_sel_hi:[1,1]
	v_pk_fma_f32 v[158:159], v[82:83], v[160:161], v[158:159]
	v_pk_mul_f32 v[158:159], v[150:151], v[158:159]
	v_lshlrev_b32_e32 v156, 16, v244
	v_lshlrev_b32_e32 v157, 16, v246
	v_pk_mul_f32 v[158:159], v[158:159], v[156:157]
	v_cvt_pk_bf16_f32 v224, v158, v159
	global_store_short v[110:111], v224, off offset:1024
	global_store_short_d16_hi v[118:119], v224, off offset:1024
	v_pk_mul_f32 v[158:159], v[250:251], v[90:91] op_sel:[0,1] op_sel_hi:[1,1]
	v_pk_fma_f32 v[158:159], v[84:85], v[160:161], v[158:159]
	v_pk_mul_f32 v[158:159], v[152:153], v[158:159]
	v_lshlrev_b32_e32 v156, 16, v245
	v_lshlrev_b32_e32 v157, 16, v247
	v_pk_mul_f32 v[158:159], v[158:159], v[156:157]
	v_cvt_pk_bf16_f32 v224, v158, v159
	global_store_short v[114:115], v224, off offset:1024
	global_store_short_d16_hi v[122:123], v224, off offset:1024
	global_load_ushort v240, v0, s[96:97] offset:3072
	global_load_ushort v242, v0, s[74:75] offset:3072
	global_load_ushort v244, v0, s[72:73] offset:3072
	global_load_ushort v246, v0, s[12:13] offset:3072
	global_load_ushort v241, v2, s[96:97] offset:3072
	global_load_ushort v243, v2, s[74:75] offset:3072
	global_load_ushort v245, v2, s[72:73] offset:3072
	global_load_ushort v247, v2, s[12:13] offset:3072
	v_add_u32_e32 v6, 0x3000, v5
	global_load_dwordx2 v[248:249], v6, s[80:81] sc1
	global_load_dwordx2 v[250:251], v6, s[50:51] sc1
	ds_read_b64 v[58:59], v7 offset:192
	ds_read_b64 v[60:61], v8 offset:12288
	ds_read_b64 v[62:63], v8 offset:45056
	ds_read_b64 v[64:65], v9 offset:12288
	ds_read_b64 v[66:67], v9 offset:45056
	s_waitcnt lgkmcnt(5)
	v_pk_mul_f32 v[222:223], v[12:13], v[10:11] op_sel:[1,1] op_sel_hi:[1,0]
	v_pk_fma_f32 v[22:23], v[12:13], v[10:11], v[222:223] op_sel:[0,0,0] op_sel_hi:[0,1,1] neg_lo:[0,0,1]
	v_pk_mul_f32 v[222:223], v[22:23], v[22:23] op_sel:[1,1] op_sel_hi:[1,0]
	v_pk_fma_f32 v[24:25], v[22:23], v[22:23], v[222:223] op_sel:[0,0,0] op_sel_hi:[0,1,1] neg_lo:[0,0,1]
	v_pk_mul_f32 v[222:223], v[24:25], v[22:23] op_sel:[1,1] op_sel_hi:[1,0]
	v_pk_fma_f32 v[26:27], v[24:25], v[22:23], v[222:223] op_sel:[0,0,0] op_sel_hi:[0,1,1] neg_lo:[0,0,1]
	v_pk_mul_f32 v[222:223], v[16:17], v[22:23] op_sel:[1,1] op_sel_hi:[0,1]
	v_pk_fma_f32 v[28:29], v[16:17], v[22:23], v[222:223] op_sel:[0,0,0] op_sel_hi:[1,0,1] neg_hi:[0,0,1]
	v_pk_mul_f32 v[222:223], v[18:19], v[24:25] op_sel:[1,1] op_sel_hi:[0,1]
	v_pk_fma_f32 v[30:31], v[18:19], v[24:25], v[222:223] op_sel:[0,0,0] op_sel_hi:[1,0,1] neg_hi:[0,0,1]
	v_pk_mul_f32 v[222:223], v[20:21], v[26:27] op_sel:[1,1] op_sel_hi:[0,1]
	v_pk_fma_f32 v[68:69], v[20:21], v[26:27], v[222:223] op_sel:[0,0,0] op_sel_hi:[1,0,1] neg_hi:[0,0,1]
	v_pk_add_f32 v[70:71], v[14:15], v[30:31]
	v_pk_add_f32 v[72:73], v[14:15], v[30:31] neg_lo:[0,1] neg_hi:[0,1]
	v_pk_add_f32 v[74:75], v[28:29], v[68:69]
	v_pk_add_f32 v[80:81], v[28:29], v[68:69] neg_lo:[0,1] neg_hi:[0,1]
	v_pk_add_f32 v[82:83], v[70:71], v[74:75]
	v_pk_add_f32 v[84:85], v[72:73], v[80:81] op_sel:[0,1] op_sel_hi:[1,0] neg_lo:[0,1]
	s_waitcnt vmcnt(14)
; __device__ __forceinline__ float bf2f(u16 h){ return __uint_as_float(((unsigned)h)<<16); }
; __device__ __forceinline__ float hconv3(const u16* __restrict__ row, int t, float w0, float w1, float w2, float bias){
;   float m = bf2f(row[t]);
;   int mi=__float_as_int(m);
;   float l=__int_as_float(__builtin_amdgcn_update_dpp(0, mi, 0x138, 0xf, 0xf, false));
;   float r=__int_as_float(__builtin_amdgcn_update_dpp(0, mi, 0x130, 0xf, 0xf, false));
;   return w0*l+w1*m+w2*r+bias;
; }
; __device__ __forceinline__ void phase_hyena(KP kp_, int hf){ asm volatile("" : "+s"(kp_)); const Params p=load_params(kp_);
;     ...
;           _Pragma("unroll 4") for (int i=0;i<8;++i){ int tb=tq+512*i; float2 xr[2]; inv12_half(Z,twA,twB,tb,xr[0],xr[1]);
;             _Pragma("unroll") for (int hh=0;hh<2;++hh){ int t=tb+hh*4096;
;               float x0=hconv3(r2,t,wb0,wb1,wb2,bb_), x1=hconv3(r2+8192,t,wb0,wb1,wb2,bb_);
;               float2 y=xr[hh]; y.x*=(1.f/16384.f); y.y*=(1.f/16384.f); float2 z1=Zs[t];
;               float o0=x0*(y.x+z1.x*bias1)*bf2f(rz[t]); float o1=x1*(y.y+z1.y*bias1)*bf2f(rz[8192+t]);
;               ybT[(size_t)c*16384+t]=f2bf(o0); ybT[(size_t)c*16384+8192+t]=f2bf(o1); } }
	v_lshlrev_b32_e32 v224, 16, v228
	v_lshlrev_b32_e32 v225, 16, v230
	v_pk_mul_f32 v[226:227], v[224:225], v[88:89] op_sel_hi:[1,0]
	v_fmac_f32_dpp v226, v224, v87 wave_shr:1 row_mask:0xf bank_mask:0xf
	v_fmac_f32_dpp v227, v225, v87 wave_shr:1 row_mask:0xf bank_mask:0xf
	v_fmac_f32_dpp v226, v224, v89 wave_shl:1 row_mask:0xf bank_mask:0xf
	v_fmac_f32_dpp v227, v225, v89 wave_shl:1 row_mask:0xf bank_mask:0xf
	v_pk_add_f32 v[150:151], v[226:227], v[90:91] op_sel_hi:[1,0]
	v_lshlrev_b32_e32 v224, 16, v229
	v_lshlrev_b32_e32 v225, 16, v231
	v_pk_mul_f32 v[226:227], v[224:225], v[88:89] op_sel_hi:[1,0]
	v_fmac_f32_dpp v226, v224, v87 wave_shr:1 row_mask:0xf bank_mask:0xf
	v_fmac_f32_dpp v227, v225, v87 wave_shr:1 row_mask:0xf bank_mask:0xf
	v_fmac_f32_dpp v226, v224, v89 wave_shl:1 row_mask:0xf bank_mask:0xf
	v_fmac_f32_dpp v227, v225, v89 wave_shl:1 row_mask:0xf bank_mask:0xf
	v_pk_add_f32 v[152:153], v[226:227], v[90:91] op_sel_hi:[1,0]
	v_pk_mul_f32 v[158:159], v[236:237], v[90:91] op_sel:[0,1] op_sel_hi:[1,1]
	v_pk_fma_f32 v[158:159], v[82:83], v[160:161], v[158:159]
	v_pk_mul_f32 v[158:159], v[150:151], v[158:159]
	v_lshlrev_b32_e32 v156, 16, v232
	v_lshlrev_b32_e32 v157, 16, v234
	v_pk_mul_f32 v[158:159], v[158:159], v[156:157]
	v_cvt_pk_bf16_f32 v224, v158, v159
	global_store_short v[110:111], v224, off offset:2048
	global_store_short_d16_hi v[118:119], v224, off offset:2048
	v_pk_mul_f32 v[158:159], v[238:239], v[90:91] op_sel:[0,1] op_sel_hi:[1,1]
	v_pk_fma_f32 v[158:159], v[84:85], v[160:161], v[158:159]
	v_pk_mul_f32 v[158:159], v[152:153], v[158:159]
	v_lshlrev_b32_e32 v156, 16, v233
	v_lshlrev_b32_e32 v157, 16, v235
	v_pk_mul_f32 v[158:159], v[158:159], v[156:157]
	v_cvt_pk_bf16_f32 v224, v158, v159
	global_store_short v[114:115], v224, off offset:2048
	global_store_short_d16_hi v[122:123], v224, off offset:2048
	global_load_ushort v228, v1, s[96:97] offset:0
	global_load_ushort v230, v1, s[74:75] offset:0
	global_load_ushort v232, v1, s[72:73] offset:0
	global_load_ushort v234, v1, s[12:13] offset:0
	global_load_ushort v229, v4, s[96:97] offset:0
	global_load_ushort v231, v4, s[74:75] offset:0
	global_load_ushort v233, v4, s[72:73] offset:0
	global_load_ushort v235, v4, s[12:13] offset:0
	v_add_u32_e32 v6, 0x4000, v5
	global_load_dwordx2 v[236:237], v6, s[80:81] sc1
	global_load_dwordx2 v[238:239], v6, s[50:51] sc1
	ds_read_b64 v[12:13], v7 offset:256
	ds_read_b64 v[14:15], v8 offset:16384
	ds_read_b64 v[16:17], v8 offset:49152
	ds_read_b64 v[18:19], v9 offset:16384
	ds_read_b64 v[20:21], v9 offset:49152
	s_waitcnt lgkmcnt(5)
	v_pk_mul_f32 v[222:223], v[58:59], v[10:11] op_sel:[1,1] op_sel_hi:[1,0]
	v_pk_fma_f32 v[22:23], v[58:59], v[10:11], v[222:223] op_sel:[0,0,0] op_sel_hi:[0,1,1] neg_lo:[0,0,1]
	v_pk_mul_f32 v[222:223], v[22:23], v[22:23] op_sel:[1,1] op_sel_hi:[1,0]
	v_pk_fma_f32 v[24:25], v[22:23], v[22:23], v[222:223] op_sel:[0,0,0] op_sel_hi:[0,1,1] neg_lo:[0,0,1]
	v_pk_mul_f32 v[222:223], v[24:25], v[22:23] op_sel:[1,1] op_sel_hi:[1,0]
	v_pk_fma_f32 v[26:27], v[24:25], v[22:23], v[222:223] op_sel:[0,0,0] op_sel_hi:[0,1,1] neg_lo:[0,0,1]
	v_pk_mul_f32 v[222:223], v[62:63], v[22:23] op_sel:[1,1] op_sel_hi:[0,1]
	v_pk_fma_f32 v[28:29], v[62:63], v[22:23], v[222:223] op_sel:[0,0,0] op_sel_hi:[1,0,1] neg_hi:[0,0,1]
	v_pk_mul_f32 v[222:223], v[64:65], v[24:25] op_sel:[1,1] op_sel_hi:[0,1]
	v_pk_fma_f32 v[30:31], v[64:65], v[24:25], v[222:223] op_sel:[0,0,0] op_sel_hi:[1,0,1] neg_hi:[0,0,1]
	v_pk_mul_f32 v[222:223], v[66:67], v[26:27] op_sel:[1,1] op_sel_hi:[0,1]
	v_pk_fma_f32 v[68:69], v[66:67], v[26:27], v[222:223] op_sel:[0,0,0] op_sel_hi:[1,0,1] neg_hi:[0,0,1]
	v_pk_add_f32 v[70:71], v[60:61], v[30:31]
	v_pk_add_f32 v[72:73], v[60:61], v[30:31] neg_lo:[0,1] neg_hi:[0,1]
	v_pk_add_f32 v[74:75], v[28:29], v[68:69]
	v_pk_add_f32 v[80:81], v[28:29], v[68:69] neg_lo:[0,1] neg_hi:[0,1]
	v_pk_add_f32 v[82:83], v[70:71], v[74:75]
	v_pk_add_f32 v[84:85], v[72:73], v[80:81] op_sel:[0,1] op_sel_hi:[1,0] neg_lo:[0,1]
	s_waitcnt vmcnt(14)
	v_lshlrev_b32_e32 v224, 16, v240
	v_lshlrev_b32_e32 v225, 16, v242
	v_pk_mul_f32 v[226:227], v[224:225], v[88:89] op_sel_hi:[1,0]
	v_fmac_f32_dpp v226, v224, v87 wave_shr:1 row_mask:0xf bank_mask:0xf
	v_fmac_f32_dpp v227, v225, v87 wave_shr:1 row_mask:0xf bank_mask:0xf
	v_fmac_f32_dpp v226, v224, v89 wave_shl:1 row_mask:0xf bank_mask:0xf
	v_fmac_f32_dpp v227, v225, v89 wave_shl:1 row_mask:0xf bank_mask:0xf
	v_pk_add_f32 v[150:151], v[226:227], v[90:91] op_sel_hi:[1,0]
	v_lshlrev_b32_e32 v224, 16, v241
	v_lshlrev_b32_e32 v225, 16, v243
	v_pk_mul_f32 v[226:227], v[224:225], v[88:89] op_sel_hi:[1,0]
	v_fmac_f32_dpp v226, v224, v87 wave_shr:1 row_mask:0xf bank_mask:0xf
	v_fmac_f32_dpp v227, v225, v87 wave_shr:1 row_mask:0xf bank_mask:0xf
	v_fmac_f32_dpp v226, v224, v89 wave_shl:1 row_mask:0xf bank_mask:0xf
	v_fmac_f32_dpp v227, v225, v89 wave_shl:1 row_mask:0xf bank_mask:0xf
	v_pk_add_f32 v[152:153], v[226:227], v[90:91] op_sel_hi:[1,0]
	v_pk_mul_f32 v[158:159], v[248:249], v[90:91] op_sel:[0,1] op_sel_hi:[1,1]
	v_pk_fma_f32 v[158:159], v[82:83], v[160:161], v[158:159]
	v_pk_mul_f32 v[158:159], v[150:151], v[158:159]
	v_lshlrev_b32_e32 v156, 16, v244
	v_lshlrev_b32_e32 v157, 16, v246
	v_pk_mul_f32 v[158:159], v[158:159], v[156:157]
	v_cvt_pk_bf16_f32 v224, v158, v159
	global_store_short v[110:111], v224, off offset:3072
	global_store_short_d16_hi v[118:119], v224, off offset:3072
	v_pk_mul_f32 v[158:159], v[250:251], v[90:91] op_sel:[0,1] op_sel_hi:[1,1]
	v_pk_fma_f32 v[158:159], v[84:85], v[160:161], v[158:159]
	v_pk_mul_f32 v[158:159], v[152:153], v[158:159]
	v_lshlrev_b32_e32 v156, 16, v245
	v_lshlrev_b32_e32 v157, 16, v247
	v_pk_mul_f32 v[158:159], v[158:159], v[156:157]
	v_cvt_pk_bf16_f32 v224, v158, v159
	global_store_short v[114:115], v224, off offset:3072
	global_store_short_d16_hi v[122:123], v224, off offset:3072
	global_load_ushort v240, v1, s[96:97] offset:1024
	global_load_ushort v242, v1, s[74:75] offset:1024
	global_load_ushort v244, v1, s[72:73] offset:1024
	global_load_ushort v246, v1, s[12:13] offset:1024
	global_load_ushort v241, v4, s[96:97] offset:1024
	global_load_ushort v243, v4, s[74:75] offset:1024
	global_load_ushort v245, v4, s[72:73] offset:1024
	global_load_ushort v247, v4, s[12:13] offset:1024
	v_add_u32_e32 v6, 0x5000, v5
	global_load_dwordx2 v[248:249], v6, s[80:81] sc1
	global_load_dwordx2 v[250:251], v6, s[50:51] sc1
	ds_read_b64 v[58:59], v7 offset:320
	ds_read_b64 v[60:61], v8 offset:20480
	ds_read_b64 v[62:63], v8 offset:53248
	ds_read_b64 v[64:65], v9 offset:20480
	ds_read_b64 v[66:67], v9 offset:53248
	s_waitcnt lgkmcnt(5)
; __device__ __forceinline__ float bf2f(u16 h){ return __uint_as_float(((unsigned)h)<<16); }
; __device__ __forceinline__ float hconv3(const u16* __restrict__ row, int t, float w0, float w1, float w2, float bias){
;   float m = bf2f(row[t]);
;   int mi=__float_as_int(m);
;   float l=__int_as_float(__builtin_amdgcn_update_dpp(0, mi, 0x138, 0xf, 0xf, false));
;   float r=__int_as_float(__builtin_amdgcn_update_dpp(0, mi, 0x130, 0xf, 0xf, false));
;   return w0*l+w1*m+w2*r+bias;
; }
; __device__ __forceinline__ void phase_hyena(KP kp_, int hf){ asm volatile("" : "+s"(kp_)); const Params p=load_params(kp_);
;     ...
;           _Pragma("unroll 4") for (int i=0;i<8;++i){ int tb=tq+512*i; float2 xr[2]; inv12_half(Z,twA,twB,tb,xr[0],xr[1]);
;             _Pragma("unroll") for (int hh=0;hh<2;++hh){ int t=tb+hh*4096;
;               float x0=hconv3(r2,t,wb0,wb1,wb2,bb_), x1=hconv3(r2+8192,t,wb0,wb1,wb2,bb_);
;               float2 y=xr[hh]; y.x*=(1.f/16384.f); y.y*=(1.f/16384.f); float2 z1=Zs[t];
;               float o0=x0*(y.x+z1.x*bias1)*bf2f(rz[t]); float o1=x1*(y.y+z1.y*bias1)*bf2f(rz[8192+t]);
;               ybT[(size_t)c*16384+t]=f2bf(o0); ybT[(size_t)c*16384+8192+t]=f2bf(o1); } }
	v_pk_mul_f32 v[222:223], v[12:13], v[10:11] op_sel:[1,1] op_sel_hi:[1,0]
	v_pk_fma_f32 v[22:23], v[12:13], v[10:11], v[222:223] op_sel:[0,0,0] op_sel_hi:[0,1,1] neg_lo:[0,0,1]
	v_pk_mul_f32 v[222:223], v[22:23], v[22:23] op_sel:[1,1] op_sel_hi:[1,0]
	v_pk_fma_f32 v[24:25], v[22:23], v[22:23], v[222:223] op_sel:[0,0,0] op_sel_hi:[0,1,1] neg_lo:[0,0,1]
	v_pk_mul_f32 v[222:223], v[24:25], v[22:23] op_sel:[1,1] op_sel_hi:[1,0]
	v_pk_fma_f32 v[26:27], v[24:25], v[22:23], v[222:223] op_sel:[0,0,0] op_sel_hi:[0,1,1] neg_lo:[0,0,1]
	v_pk_mul_f32 v[222:223], v[16:17], v[22:23] op_sel:[1,1] op_sel_hi:[0,1]
	v_pk_fma_f32 v[28:29], v[16:17], v[22:23], v[222:223] op_sel:[0,0,0] op_sel_hi:[1,0,1] neg_hi:[0,0,1]
	v_pk_mul_f32 v[222:223], v[18:19], v[24:25] op_sel:[1,1] op_sel_hi:[0,1]
	v_pk_fma_f32 v[30:31], v[18:19], v[24:25], v[222:223] op_sel:[0,0,0] op_sel_hi:[1,0,1] neg_hi:[0,0,1]
	v_pk_mul_f32 v[222:223], v[20:21], v[26:27] op_sel:[1,1] op_sel_hi:[0,1]
	v_pk_fma_f32 v[68:69], v[20:21], v[26:27], v[222:223] op_sel:[0,0,0] op_sel_hi:[1,0,1] neg_hi:[0,0,1]
	v_pk_add_f32 v[70:71], v[14:15], v[30:31]
	v_pk_add_f32 v[72:73], v[14:15], v[30:31] neg_lo:[0,1] neg_hi:[0,1]
	v_pk_add_f32 v[74:75], v[28:29], v[68:69]
	v_pk_add_f32 v[80:81], v[28:29], v[68:69] neg_lo:[0,1] neg_hi:[0,1]
	v_pk_add_f32 v[82:83], v[70:71], v[74:75]
	v_pk_add_f32 v[84:85], v[72:73], v[80:81] op_sel:[0,1] op_sel_hi:[1,0] neg_lo:[0,1]
	s_waitcnt vmcnt(14)
	v_lshlrev_b32_e32 v224, 16, v228
	v_lshlrev_b32_e32 v225, 16, v230
	v_pk_mul_f32 v[226:227], v[224:225], v[88:89] op_sel_hi:[1,0]
	v_fmac_f32_dpp v226, v224, v87 wave_shr:1 row_mask:0xf bank_mask:0xf
	v_fmac_f32_dpp v227, v225, v87 wave_shr:1 row_mask:0xf bank_mask:0xf
	v_fmac_f32_dpp v226, v224, v89 wave_shl:1 row_mask:0xf bank_mask:0xf
	v_fmac_f32_dpp v227, v225, v89 wave_shl:1 row_mask:0xf bank_mask:0xf
	v_pk_add_f32 v[150:151], v[226:227], v[90:91] op_sel_hi:[1,0]
	v_lshlrev_b32_e32 v224, 16, v229
	v_lshlrev_b32_e32 v225, 16, v231
	v_pk_mul_f32 v[226:227], v[224:225], v[88:89] op_sel_hi:[1,0]
	v_fmac_f32_dpp v226, v224, v87 wave_shr:1 row_mask:0xf bank_mask:0xf
	v_fmac_f32_dpp v227, v225, v87 wave_shr:1 row_mask:0xf bank_mask:0xf
	v_fmac_f32_dpp v226, v224, v89 wave_shl:1 row_mask:0xf bank_mask:0xf
	v_fmac_f32_dpp v227, v225, v89 wave_shl:1 row_mask:0xf bank_mask:0xf
	v_pk_add_f32 v[152:153], v[226:227], v[90:91] op_sel_hi:[1,0]
	v_pk_mul_f32 v[158:159], v[236:237], v[90:91] op_sel:[0,1] op_sel_hi:[1,1]
	v_pk_fma_f32 v[158:159], v[82:83], v[160:161], v[158:159]
	v_pk_mul_f32 v[158:159], v[150:151], v[158:159]
	v_lshlrev_b32_e32 v156, 16, v232
	v_lshlrev_b32_e32 v157, 16, v234
	v_pk_mul_f32 v[158:159], v[158:159], v[156:157]
	v_cvt_pk_bf16_f32 v224, v158, v159
	global_store_short v[112:113], v224, off offset:0
	global_store_short_d16_hi v[120:121], v224, off offset:0
	v_pk_mul_f32 v[158:159], v[238:239], v[90:91] op_sel:[0,1] op_sel_hi:[1,1]
	v_pk_fma_f32 v[158:159], v[84:85], v[160:161], v[158:159]
	v_pk_mul_f32 v[158:159], v[152:153], v[158:159]
	v_lshlrev_b32_e32 v156, 16, v233
	v_lshlrev_b32_e32 v157, 16, v235
	v_pk_mul_f32 v[158:159], v[158:159], v[156:157]
	v_cvt_pk_bf16_f32 v224, v158, v159
	global_store_short v[116:117], v224, off offset:0
	global_store_short_d16_hi v[124:125], v224, off offset:0
	global_load_ushort v228, v1, s[96:97] offset:2048
	global_load_ushort v230, v1, s[74:75] offset:2048
	global_load_ushort v232, v1, s[72:73] offset:2048
	global_load_ushort v234, v1, s[12:13] offset:2048
	global_load_ushort v229, v4, s[96:97] offset:2048
	global_load_ushort v231, v4, s[74:75] offset:2048
	global_load_ushort v233, v4, s[72:73] offset:2048
	global_load_ushort v235, v4, s[12:13] offset:2048
	v_add_u32_e32 v6, 0x6000, v5
	global_load_dwordx2 v[236:237], v6, s[80:81] sc1
	global_load_dwordx2 v[238:239], v6, s[50:51] sc1
	ds_read_b64 v[12:13], v7 offset:384
	ds_read_b64 v[14:15], v8 offset:24576
	ds_read_b64 v[16:17], v8 offset:57344
	ds_read_b64 v[18:19], v9 offset:24576
	ds_read_b64 v[20:21], v9 offset:57344
	s_waitcnt lgkmcnt(5)
	v_pk_mul_f32 v[222:223], v[58:59], v[10:11] op_sel:[1,1] op_sel_hi:[1,0]
	v_pk_fma_f32 v[22:23], v[58:59], v[10:11], v[222:223] op_sel:[0,0,0] op_sel_hi:[0,1,1] neg_lo:[0,0,1]
	v_pk_mul_f32 v[222:223], v[22:23], v[22:23] op_sel:[1,1] op_sel_hi:[1,0]
	v_pk_fma_f32 v[24:25], v[22:23], v[22:23], v[222:223] op_sel:[0,0,0] op_sel_hi:[0,1,1] neg_lo:[0,0,1]
	v_pk_mul_f32 v[222:223], v[24:25], v[22:23] op_sel:[1,1] op_sel_hi:[1,0]
	v_pk_fma_f32 v[26:27], v[24:25], v[22:23], v[222:223] op_sel:[0,0,0] op_sel_hi:[0,1,1] neg_lo:[0,0,1]
	v_pk_mul_f32 v[222:223], v[62:63], v[22:23] op_sel:[1,1] op_sel_hi:[0,1]
	v_pk_fma_f32 v[28:29], v[62:63], v[22:23], v[222:223] op_sel:[0,0,0] op_sel_hi:[1,0,1] neg_hi:[0,0,1]
	v_pk_mul_f32 v[222:223], v[64:65], v[24:25] op_sel:[1,1] op_sel_hi:[0,1]
	v_pk_fma_f32 v[30:31], v[64:65], v[24:25], v[222:223] op_sel:[0,0,0] op_sel_hi:[1,0,1] neg_hi:[0,0,1]
	v_pk_mul_f32 v[222:223], v[66:67], v[26:27] op_sel:[1,1] op_sel_hi:[0,1]
	v_pk_fma_f32 v[68:69], v[66:67], v[26:27], v[222:223] op_sel:[0,0,0] op_sel_hi:[1,0,1] neg_hi:[0,0,1]
	v_pk_add_f32 v[70:71], v[60:61], v[30:31]
	v_pk_add_f32 v[72:73], v[60:61], v[30:31] neg_lo:[0,1] neg_hi:[0,1]
	v_pk_add_f32 v[74:75], v[28:29], v[68:69]
	v_pk_add_f32 v[80:81], v[28:29], v[68:69] neg_lo:[0,1] neg_hi:[0,1]
	v_pk_add_f32 v[82:83], v[70:71], v[74:75]
	v_pk_add_f32 v[84:85], v[72:73], v[80:81] op_sel:[0,1] op_sel_hi:[1,0] neg_lo:[0,1]
	s_waitcnt vmcnt(14)
; __device__ __forceinline__ float bf2f(u16 h){ return __uint_as_float(((unsigned)h)<<16); }
; __device__ __forceinline__ float hconv3(const u16* __restrict__ row, int t, float w0, float w1, float w2, float bias){
;   float m = bf2f(row[t]);
;   int mi=__float_as_int(m);
;   float l=__int_as_float(__builtin_amdgcn_update_dpp(0, mi, 0x138, 0xf, 0xf, false));
;   float r=__int_as_float(__builtin_amdgcn_update_dpp(0, mi, 0x130, 0xf, 0xf, false));
;   return w0*l+w1*m+w2*r+bias;
; }
; __device__ __forceinline__ void phase_hyena(KP kp_, int hf){ asm volatile("" : "+s"(kp_)); const Params p=load_params(kp_);
;     ...
;           _Pragma("unroll 4") for (int i=0;i<8;++i){ int tb=tq+512*i; float2 xr[2]; inv12_half(Z,twA,twB,tb,xr[0],xr[1]);
;             _Pragma("unroll") for (int hh=0;hh<2;++hh){ int t=tb+hh*4096;
;               float x0=hconv3(r2,t,wb0,wb1,wb2,bb_), x1=hconv3(r2+8192,t,wb0,wb1,wb2,bb_);
;               float2 y=xr[hh]; y.x*=(1.f/16384.f); y.y*=(1.f/16384.f); float2 z1=Zs[t];
;               float o0=x0*(y.x+z1.x*bias1)*bf2f(rz[t]); float o1=x1*(y.y+z1.y*bias1)*bf2f(rz[8192+t]);
;               ybT[(size_t)c*16384+t]=f2bf(o0); ybT[(size_t)c*16384+8192+t]=f2bf(o1); } }
	v_lshlrev_b32_e32 v224, 16, v240
	v_lshlrev_b32_e32 v225, 16, v242
	v_pk_mul_f32 v[226:227], v[224:225], v[88:89] op_sel_hi:[1,0]
	v_fmac_f32_dpp v226, v224, v87 wave_shr:1 row_mask:0xf bank_mask:0xf
	v_fmac_f32_dpp v227, v225, v87 wave_shr:1 row_mask:0xf bank_mask:0xf
	v_fmac_f32_dpp v226, v224, v89 wave_shl:1 row_mask:0xf bank_mask:0xf
	v_fmac_f32_dpp v227, v225, v89 wave_shl:1 row_mask:0xf bank_mask:0xf
	v_pk_add_f32 v[150:151], v[226:227], v[90:91] op_sel_hi:[1,0]
	v_lshlrev_b32_e32 v224, 16, v241
	v_lshlrev_b32_e32 v225, 16, v243
	v_pk_mul_f32 v[226:227], v[224:225], v[88:89] op_sel_hi:[1,0]
	v_fmac_f32_dpp v226, v224, v87 wave_shr:1 row_mask:0xf bank_mask:0xf
	v_fmac_f32_dpp v227, v225, v87 wave_shr:1 row_mask:0xf bank_mask:0xf
	v_fmac_f32_dpp v226, v224, v89 wave_shl:1 row_mask:0xf bank_mask:0xf
	v_fmac_f32_dpp v227, v225, v89 wave_shl:1 row_mask:0xf bank_mask:0xf
	v_pk_add_f32 v[152:153], v[226:227], v[90:91] op_sel_hi:[1,0]
	v_pk_mul_f32 v[158:159], v[248:249], v[90:91] op_sel:[0,1] op_sel_hi:[1,1]
	v_pk_fma_f32 v[158:159], v[82:83], v[160:161], v[158:159]
	v_pk_mul_f32 v[158:159], v[150:151], v[158:159]
	v_lshlrev_b32_e32 v156, 16, v244
	v_lshlrev_b32_e32 v157, 16, v246
	v_pk_mul_f32 v[158:159], v[158:159], v[156:157]
	v_cvt_pk_bf16_f32 v224, v158, v159
	global_store_short v[112:113], v224, off offset:1024
	global_store_short_d16_hi v[120:121], v224, off offset:1024
	v_pk_mul_f32 v[158:159], v[250:251], v[90:91] op_sel:[0,1] op_sel_hi:[1,1]
	v_pk_fma_f32 v[158:159], v[84:85], v[160:161], v[158:159]
	v_pk_mul_f32 v[158:159], v[152:153], v[158:159]
	v_lshlrev_b32_e32 v156, 16, v245
	v_lshlrev_b32_e32 v157, 16, v247
	v_pk_mul_f32 v[158:159], v[158:159], v[156:157]
	v_cvt_pk_bf16_f32 v224, v158, v159
	global_store_short v[116:117], v224, off offset:1024
	global_store_short_d16_hi v[124:125], v224, off offset:1024
	global_load_ushort v240, v1, s[96:97] offset:3072
	global_load_ushort v242, v1, s[74:75] offset:3072
	global_load_ushort v244, v1, s[72:73] offset:3072
	global_load_ushort v246, v1, s[12:13] offset:3072
	global_load_ushort v241, v4, s[96:97] offset:3072
	global_load_ushort v243, v4, s[74:75] offset:3072
	global_load_ushort v245, v4, s[72:73] offset:3072
	global_load_ushort v247, v4, s[12:13] offset:3072
	v_add_u32_e32 v6, 0x7000, v5
	global_load_dwordx2 v[248:249], v6, s[80:81] sc1
	global_load_dwordx2 v[250:251], v6, s[50:51] sc1
	ds_read_b64 v[58:59], v7 offset:448
	ds_read_b64 v[60:61], v8 offset:28672
	ds_read_b64 v[62:63], v8 offset:61440
	ds_read_b64 v[64:65], v9 offset:28672
	ds_read_b64 v[66:67], v9 offset:61440
	s_waitcnt lgkmcnt(5)
	v_pk_mul_f32 v[222:223], v[12:13], v[10:11] op_sel:[1,1] op_sel_hi:[1,0]
	v_pk_fma_f32 v[22:23], v[12:13], v[10:11], v[222:223] op_sel:[0,0,0] op_sel_hi:[0,1,1] neg_lo:[0,0,1]
	v_pk_mul_f32 v[222:223], v[22:23], v[22:23] op_sel:[1,1] op_sel_hi:[1,0]
	v_pk_fma_f32 v[24:25], v[22:23], v[22:23], v[222:223] op_sel:[0,0,0] op_sel_hi:[0,1,1] neg_lo:[0,0,1]
	v_pk_mul_f32 v[222:223], v[24:25], v[22:23] op_sel:[1,1] op_sel_hi:[1,0]
	v_pk_fma_f32 v[26:27], v[24:25], v[22:23], v[222:223] op_sel:[0,0,0] op_sel_hi:[0,1,1] neg_lo:[0,0,1]
	v_pk_mul_f32 v[222:223], v[16:17], v[22:23] op_sel:[1,1] op_sel_hi:[0,1]
	v_pk_fma_f32 v[28:29], v[16:17], v[22:23], v[222:223] op_sel:[0,0,0] op_sel_hi:[1,0,1] neg_hi:[0,0,1]
	v_pk_mul_f32 v[222:223], v[18:19], v[24:25] op_sel:[1,1] op_sel_hi:[0,1]
	v_pk_fma_f32 v[30:31], v[18:19], v[24:25], v[222:223] op_sel:[0,0,0] op_sel_hi:[1,0,1] neg_hi:[0,0,1]
	v_pk_mul_f32 v[222:223], v[20:21], v[26:27] op_sel:[1,1] op_sel_hi:[0,1]
	v_pk_fma_f32 v[68:69], v[20:21], v[26:27], v[222:223] op_sel:[0,0,0] op_sel_hi:[1,0,1] neg_hi:[0,0,1]
	v_pk_add_f32 v[70:71], v[14:15], v[30:31]
	v_pk_add_f32 v[72:73], v[14:15], v[30:31] neg_lo:[0,1] neg_hi:[0,1]
	v_pk_add_f32 v[74:75], v[28:29], v[68:69]
	v_pk_add_f32 v[80:81], v[28:29], v[68:69] neg_lo:[0,1] neg_hi:[0,1]
	v_pk_add_f32 v[82:83], v[70:71], v[74:75]
	v_pk_add_f32 v[84:85], v[72:73], v[80:81] op_sel:[0,1] op_sel_hi:[1,0] neg_lo:[0,1]
	s_waitcnt vmcnt(14)
; __device__ __forceinline__ float bf2f(u16 h){ return __uint_as_float(((unsigned)h)<<16); }
; __device__ __forceinline__ float hconv3(const u16* __restrict__ row, int t, float w0, float w1, float w2, float bias){
;   float m = bf2f(row[t]);
;   int mi=__float_as_int(m);
;   float l=__int_as_float(__builtin_amdgcn_update_dpp(0, mi, 0x138, 0xf, 0xf, false));
;   float r=__int_as_float(__builtin_amdgcn_update_dpp(0, mi, 0x130, 0xf, 0xf, false));
;   return w0*l+w1*m+w2*r+bias;
; }
; __device__ __forceinline__ void phase_hyena(KP kp_, int hf){ asm volatile("" : "+s"(kp_)); const Params p=load_params(kp_);
;     ...
;           _Pragma("unroll 4") for (int i=0;i<8;++i){ int tb=tq+512*i; float2 xr[2]; inv12_half(Z,twA,twB,tb,xr[0],xr[1]);
;             _Pragma("unroll") for (int hh=0;hh<2;++hh){ int t=tb+hh*4096;
;               float x0=hconv3(r2,t,wb0,wb1,wb2,bb_), x1=hconv3(r2+8192,t,wb0,wb1,wb2,bb_);
;               float2 y=xr[hh]; y.x*=(1.f/16384.f); y.y*=(1.f/16384.f); float2 z1=Zs[t];
;               float o0=x0*(y.x+z1.x*bias1)*bf2f(rz[t]); float o1=x1*(y.y+z1.y*bias1)*bf2f(rz[8192+t]);
;               ybT[(size_t)c*16384+t]=f2bf(o0); ybT[(size_t)c*16384+8192+t]=f2bf(o1); } }
	v_lshlrev_b32_e32 v224, 16, v228
	v_lshlrev_b32_e32 v225, 16, v230
	v_pk_mul_f32 v[226:227], v[224:225], v[88:89] op_sel_hi:[1,0]
	v_fmac_f32_dpp v226, v224, v87 wave_shr:1 row_mask:0xf bank_mask:0xf
	v_fmac_f32_dpp v227, v225, v87 wave_shr:1 row_mask:0xf bank_mask:0xf
	v_fmac_f32_dpp v226, v224, v89 wave_shl:1 row_mask:0xf bank_mask:0xf
	v_fmac_f32_dpp v227, v225, v89 wave_shl:1 row_mask:0xf bank_mask:0xf
	v_pk_add_f32 v[150:151], v[226:227], v[90:91] op_sel_hi:[1,0]
	v_lshlrev_b32_e32 v224, 16, v229
	v_lshlrev_b32_e32 v225, 16, v231
	v_pk_mul_f32 v[226:227], v[224:225], v[88:89] op_sel_hi:[1,0]
	v_fmac_f32_dpp v226, v224, v87 wave_shr:1 row_mask:0xf bank_mask:0xf
	v_fmac_f32_dpp v227, v225, v87 wave_shr:1 row_mask:0xf bank_mask:0xf
	v_fmac_f32_dpp v226, v224, v89 wave_shl:1 row_mask:0xf bank_mask:0xf
	v_fmac_f32_dpp v227, v225, v89 wave_shl:1 row_mask:0xf bank_mask:0xf
	v_pk_add_f32 v[152:153], v[226:227], v[90:91] op_sel_hi:[1,0]
	v_pk_mul_f32 v[158:159], v[236:237], v[90:91] op_sel:[0,1] op_sel_hi:[1,1]
	v_pk_fma_f32 v[158:159], v[82:83], v[160:161], v[158:159]
	v_pk_mul_f32 v[158:159], v[150:151], v[158:159]
	v_lshlrev_b32_e32 v156, 16, v232
	v_lshlrev_b32_e32 v157, 16, v234
	v_pk_mul_f32 v[158:159], v[158:159], v[156:157]
	v_cvt_pk_bf16_f32 v224, v158, v159
	global_store_short v[112:113], v224, off offset:2048
	global_store_short_d16_hi v[120:121], v224, off offset:2048
	v_pk_mul_f32 v[158:159], v[238:239], v[90:91] op_sel:[0,1] op_sel_hi:[1,1]
	v_pk_fma_f32 v[158:159], v[84:85], v[160:161], v[158:159]
	v_pk_mul_f32 v[158:159], v[152:153], v[158:159]
	v_lshlrev_b32_e32 v156, 16, v233
	v_lshlrev_b32_e32 v157, 16, v235
	v_pk_mul_f32 v[158:159], v[158:159], v[156:157]
	v_cvt_pk_bf16_f32 v224, v158, v159
	global_store_short v[116:117], v224, off offset:2048
	global_store_short_d16_hi v[124:125], v224, off offset:2048
	s_waitcnt lgkmcnt(0)
	v_pk_mul_f32 v[222:223], v[58:59], v[10:11] op_sel:[1,1] op_sel_hi:[1,0]
	v_pk_fma_f32 v[22:23], v[58:59], v[10:11], v[222:223] op_sel:[0,0,0] op_sel_hi:[0,1,1] neg_lo:[0,0,1]
	v_pk_mul_f32 v[222:223], v[22:23], v[22:23] op_sel:[1,1] op_sel_hi:[1,0]
	v_pk_fma_f32 v[24:25], v[22:23], v[22:23], v[222:223] op_sel:[0,0,0] op_sel_hi:[0,1,1] neg_lo:[0,0,1]
	v_pk_mul_f32 v[222:223], v[24:25], v[22:23] op_sel:[1,1] op_sel_hi:[1,0]
	v_pk_fma_f32 v[26:27], v[24:25], v[22:23], v[222:223] op_sel:[0,0,0] op_sel_hi:[0,1,1] neg_lo:[0,0,1]
	v_pk_mul_f32 v[222:223], v[62:63], v[22:23] op_sel:[1,1] op_sel_hi:[0,1]
	v_pk_fma_f32 v[28:29], v[62:63], v[22:23], v[222:223] op_sel:[0,0,0] op_sel_hi:[1,0,1] neg_hi:[0,0,1]
	v_pk_mul_f32 v[222:223], v[64:65], v[24:25] op_sel:[1,1] op_sel_hi:[0,1]
	v_pk_fma_f32 v[30:31], v[64:65], v[24:25], v[222:223] op_sel:[0,0,0] op_sel_hi:[1,0,1] neg_hi:[0,0,1]
	v_pk_mul_f32 v[222:223], v[66:67], v[26:27] op_sel:[1,1] op_sel_hi:[0,1]
	v_pk_fma_f32 v[68:69], v[66:67], v[26:27], v[222:223] op_sel:[0,0,0] op_sel_hi:[1,0,1] neg_hi:[0,0,1]
	v_pk_add_f32 v[70:71], v[60:61], v[30:31]
	v_pk_add_f32 v[72:73], v[60:61], v[30:31] neg_lo:[0,1] neg_hi:[0,1]
	v_pk_add_f32 v[74:75], v[28:29], v[68:69]
	v_pk_add_f32 v[80:81], v[28:29], v[68:69] neg_lo:[0,1] neg_hi:[0,1]
	v_pk_add_f32 v[82:83], v[70:71], v[74:75]
	v_pk_add_f32 v[84:85], v[72:73], v[80:81] op_sel:[0,1] op_sel_hi:[1,0] neg_lo:[0,1]
	s_waitcnt vmcnt(4)
	v_lshlrev_b32_e32 v224, 16, v240
	v_lshlrev_b32_e32 v225, 16, v242
	v_pk_mul_f32 v[226:227], v[224:225], v[88:89] op_sel_hi:[1,0]
	v_fmac_f32_dpp v226, v224, v87 wave_shr:1 row_mask:0xf bank_mask:0xf
	v_fmac_f32_dpp v227, v225, v87 wave_shr:1 row_mask:0xf bank_mask:0xf
	v_fmac_f32_dpp v226, v224, v89 wave_shl:1 row_mask:0xf bank_mask:0xf
	v_fmac_f32_dpp v227, v225, v89 wave_shl:1 row_mask:0xf bank_mask:0xf
	v_pk_add_f32 v[150:151], v[226:227], v[90:91] op_sel_hi:[1,0]
	v_lshlrev_b32_e32 v224, 16, v241
	v_lshlrev_b32_e32 v225, 16, v243
	v_pk_mul_f32 v[226:227], v[224:225], v[88:89] op_sel_hi:[1,0]
	v_fmac_f32_dpp v226, v224, v87 wave_shr:1 row_mask:0xf bank_mask:0xf
	v_fmac_f32_dpp v227, v225, v87 wave_shr:1 row_mask:0xf bank_mask:0xf
	v_fmac_f32_dpp v226, v224, v89 wave_shl:1 row_mask:0xf bank_mask:0xf
	v_fmac_f32_dpp v227, v225, v89 wave_shl:1 row_mask:0xf bank_mask:0xf
	v_pk_add_f32 v[152:153], v[226:227], v[90:91] op_sel_hi:[1,0]
	v_pk_mul_f32 v[158:159], v[248:249], v[90:91] op_sel:[0,1] op_sel_hi:[1,1]
	v_pk_fma_f32 v[158:159], v[82:83], v[160:161], v[158:159]
	v_pk_mul_f32 v[158:159], v[150:151], v[158:159]
	v_lshlrev_b32_e32 v156, 16, v244
	v_lshlrev_b32_e32 v157, 16, v246
	v_pk_mul_f32 v[158:159], v[158:159], v[156:157]
	v_cvt_pk_bf16_f32 v224, v158, v159
	global_store_short v[112:113], v224, off offset:3072
	global_store_short_d16_hi v[120:121], v224, off offset:3072
	v_pk_mul_f32 v[158:159], v[250:251], v[90:91] op_sel:[0,1] op_sel_hi:[1,1]
	v_pk_fma_f32 v[158:159], v[84:85], v[160:161], v[158:159]
	v_pk_mul_f32 v[158:159], v[152:153], v[158:159]
	v_lshlrev_b32_e32 v156, 16, v245
	v_lshlrev_b32_e32 v157, 16, v247
	v_pk_mul_f32 v[158:159], v[158:159], v[156:157]
	v_cvt_pk_bf16_f32 v224, v158, v159
	global_store_short v[116:117], v224, off offset:3072
	global_store_short_d16_hi v[124:125], v224, off offset:3072
	s_mov_b32 s50, 0x2000
	s_mov_b32 s51, 0
	s_mov_b64 s[12:13], 0
